# plus phase-1 V tiles: transposed VT dwordx2 store pairs (32 B apart) merged into dwordx4
# speedup vs baseline: 1.0148x; 1.0041x over previous
; DI int BIDX() { int b = blockIdx.x; asm volatile("" : "+s"(b)); return b; }
; #define GL_LOAD(s_, kt_) if (VAR != 1) { a##s_##0 = GL_A(0, kt_); a##s_##1 = GL_A(1, kt_); a##s_##2 = GL_A(2, kt_); a##s_##3 = GL_A(3, kt_); b##s_##0 = GL_B(0, kt_); b##s_##1 = GL_B(1, kt_); b##s_##2 = GL_B(2, kt_); b##s_##3 = GL_B(3, kt_); }
; #define LDS_STORE(s_, buf_) if (VAR != 2) { LDS_ST1(sA, 0, buf_, a##s_##0) LDS_ST1(sA, 1, buf_, a##s_##1) LDS_ST1(sA, 2, buf_, a##s_##2) LDS_ST1(sA, 3, buf_, a##s_##3) LDS_ST1(sB, 0, buf_, b##s_##0) LDS_ST1(sB, 1, buf_, b##s_##1) LDS_ST1(sB, 2, buf_, b##s_##2) LDS_ST1(sB, 3, buf_, b##s_##3) }
; DI int tile_groups(int MT, int NT) { return (MT >> 6) * ((NT + 7) >> 3) * 512; }
;     ...
;   GL_LOAD(0, 0)
;   GL_LOAD(1, 1)
;   LDS_STORE(0, 0)
;   if (VAR != 4) __syncthreads();
; #pragma unroll
;   for (int kt = 0; kt < nk; kt += 2) {
;     if (kt + 2 < nk) { GL_LOAD(0, kt + 2) }
;     MMA_TILE(0)
;     LDS_STORE(1, 1)
;     if (VAR != 4) __syncthreads();
; DI void phase_proj(const Params& P, int l, char* smem) {
;     ...
;   for (int vb = BIDX(); vb < tile_groups(128, 63); vb += gridDim.x) {
;     int tm, tn; if (!tile_of(vb, 128, 63, tm, tn)) continue;
;     const int m0 = tm * 128, n0 = tn * 128;
;     f32x4 acc[4][4]; zero_acc(acc);
;     const int row0 = m0 + wm * 64, col0 = n0 + wn * 64;
;     float rs[4]; load_rstd(rs, ssq, row0, lr);
;     if (n0 >= PW) {
;       gemm_kloop<false, false, 16>(acc, xb + (size_t)m0 * DM, DM, Wt + (size_t)n0 * DM, DM, smem);
;       const int cb = col0 - PW;
;       const int br = cb >> 9, c0 = cb & 511;
;       const int b = row0 >> 12, s0 = row0 & 4095;
.LBB0_691:
	s_and_b64 vcc, exec, s[4:5]
	s_cbranch_vccz .LBB0_636
	v_mov_b32_e32 v18, v148
	s_mov_b32 s17, s27
	s_lshl_b64 s[4:5], s[16:17], 11
	v_ashrrev_i32_e32 v16, 3, v18
	v_readlane_b32 s1, v252, 19
	v_ashrrev_i32_e32 v17, 31, v16
	v_add_u32_e32 v54, 64, v16
	s_add_u32 s4, s1, s4
	v_readlane_b32 s1, v252, 20
	v_lshlrev_b64 v[6:7], 11, v[16:17]
	v_lshlrev_b32_e32 v17, 4, v18
	v_add_u32_e32 v20, 32, v16
	v_ashrrev_i32_e32 v55, 31, v54
	s_addc_u32 s5, s1, s5
	v_lshl_add_u64 v[0:1], s[18:19], 0, v[6:7]
	v_and_b32_e32 v150, 0x70, v17
	v_ashrrev_i32_e32 v21, 31, v20
	v_lshlrev_b64 v[12:13], 11, v[54:55]
	v_lshl_add_u64 v[0:1], v[0:1], 0, v[150:151]
	v_lshlrev_b64 v[10:11], 11, v[20:21]
	v_lshl_add_u64 v[4:5], s[18:19], 0, v[12:13]
	v_add_u32_e32 v56, 0x60, v16
	v_lshl_add_u64 v[6:7], s[4:5], 0, v[6:7]
	global_load_dwordx4 v[22:25], v[0:1], off
	v_lshl_add_u64 v[2:3], s[18:19], 0, v[10:11]
	v_lshl_add_u64 v[4:5], v[4:5], 0, v[150:151]
	v_ashrrev_i32_e32 v57, 31, v56
	v_lshl_add_u64 v[6:7], v[6:7], 0, v[150:151]
	v_lshl_add_u64 v[2:3], v[2:3], 0, v[150:151]
	global_load_dwordx4 v[30:33], v[4:5], off
	global_load_dwordx4 v[38:41], v[6:7], off
	v_lshlrev_b64 v[14:15], 11, v[56:57]
	global_load_dwordx4 v[26:29], v[2:3], off
	v_lshl_add_u64 v[8:9], s[18:19], 0, v[14:15]
	v_lshl_add_u64 v[8:9], v[8:9], 0, v[150:151]
	v_lshl_add_u64 v[10:11], s[4:5], 0, v[10:11]
	global_load_dwordx4 v[34:37], v[8:9], off
	v_lshl_add_u64 v[10:11], v[10:11], 0, v[150:151]
	v_lshl_add_u64 v[12:13], s[4:5], 0, v[12:13]
	global_load_dwordx4 v[42:45], v[10:11], off
	v_lshl_add_u64 v[12:13], v[12:13], 0, v[150:151]
	v_lshl_add_u64 v[14:15], s[4:5], 0, v[14:15]
	global_load_dwordx4 v[46:49], v[12:13], off
	v_lshl_add_u64 v[14:15], v[14:15], 0, v[150:151]
	global_load_dwordx4 v[50:53], v[14:15], off
	v_and_b32_e32 v19, 15, v18
	v_lshrrev_b32_e32 v55, 1, v18
	v_lshlrev_b32_e32 v21, 3, v18
	s_movk_i32 s1, 0x70
	v_and_or_b32 v55, v55, s29, v19
	v_and_b32_e32 v82, 48, v18
	v_and_b32_e32 v57, 0x70, v21
	v_bitop3_b32 v17, v17, s1, v18 bitop3:0x48
	v_lshlrev_b32_e32 v95, 7, v55
	v_lshlrev_b32_e32 v83, 7, v18
	v_lshl_or_b32 v18, v16, 7, v17
	v_lshl_or_b32 v19, v20, 7, v17
	v_lshl_or_b32 v20, v54, 7, v17
	v_lshl_or_b32 v17, v56, 7, v17
	v_bitop3_b32 v16, v95, v57, v82 bitop3:0xf6
	global_load_dwordx4 v[54:57], v[0:1], off offset:128
	global_load_dwordx4 v[58:61], v[6:7], off offset:128
	global_load_dwordx4 v[62:65], v[2:3], off offset:128
	global_load_dwordx4 v[66:69], v[4:5], off offset:128
	global_load_dwordx4 v[70:73], v[8:9], off offset:128
	global_load_dwordx4 v[74:77], v[10:11], off offset:128
	global_load_dwordx4 v[78:81], v[12:13], off offset:128
	global_load_dwordx4 v[104:107], v[14:15], off offset:128
	v_bitop3_b32 v21, v21, v82, s1 bitop3:0x6c
	v_add_u32_e32 v94, 0xffffe680, v94
	s_movk_i32 s1, 0x1c0
	v_and_or_b32 v103, v175, 64, v84
	s_mov_b64 s[4:5], 0x60
	s_waitcnt vmcnt(15)
	ds_write_b128 v18, v[22:25]
	s_waitcnt vmcnt(13)
	ds_write_b128 v18, v[38:41] offset:32768
	s_waitcnt vmcnt(12)
	ds_write_b128 v19, v[26:29]
	ds_write_b128 v20, v[30:33]
	s_waitcnt vmcnt(11)
	ds_write_b128 v17, v[34:37]
	s_waitcnt vmcnt(10)
	ds_write_b128 v19, v[42:45] offset:32768
	s_waitcnt vmcnt(9)
	ds_write_b128 v20, v[46:49] offset:32768
	s_waitcnt vmcnt(8)
	ds_write_b128 v17, v[50:53] offset:32768
	s_waitcnt lgkmcnt(0)
	s_barrier
	s_setprio 1
	ds_read_b128 v[22:25], v16
	v_and_b32_e32 v26, 0x2780, v83
	v_or_b32_e32 v28, v26, v21
	ds_read_b128 v[30:33], v28 offset:32768
	s_waitcnt lgkmcnt(0)
	v_mfma_f32_16x16x32_f16 v[42:45], v[22:25], v[30:33], 0
	ds_read_b128 v[34:37], v16 offset:2048
	s_waitcnt lgkmcnt(0)
	v_mfma_f32_16x16x32_f16 v[116:119], v[34:37], v[30:33], 0
	ds_read_b128 v[38:41], v28 offset:34816
	ds_read_b128 v[128:131], v16 offset:4096
	s_waitcnt lgkmcnt(0)
	v_mfma_f32_16x16x32_f16 v[136:139], v[128:131], v[30:33], 0
	ds_read_b128 v[50:53], v28 offset:36864
	ds_read_b128 v[132:135], v16 offset:6144
	s_waitcnt lgkmcnt(0)
	v_mfma_f32_16x16x32_f16 v[154:157], v[132:135], v[30:33], 0
	ds_read_b128 v[108:111], v28 offset:38912
	v_mfma_f32_16x16x32_f16 v[46:49], v[22:25], v[38:41], 0
	v_bitop3_b32 v29, v95, v21, 64 bitop3:0xf6
	v_mfma_f32_16x16x32_f16 v[112:115], v[22:25], v[50:53], 0
	ds_read_b128 v[158:161], v29
	s_waitcnt lgkmcnt(1)
	v_mfma_f32_16x16x32_f16 v[22:25], v[22:25], v[108:111], 0
	ds_read_b128 v[162:165], v29 offset:2048
	v_mfma_f32_16x16x32_f16 v[120:123], v[34:37], v[38:41], 0
	v_xor_b32_e32 v21, 64, v21
	v_mfma_f32_16x16x32_f16 v[124:127], v[34:37], v[50:53], 0
	v_ashrrev_i32_e32 v95, 12, v99
	v_mfma_f32_16x16x32_f16 v[34:37], v[34:37], v[108:111], 0
	v_and_b32_e32 v99, 0xfc0, v99
	v_mfma_f32_16x16x32_f16 v[140:143], v[128:131], v[38:41], 0
	v_lshlrev_b32_e32 v150, 1, v99
	v_or_b32_e32 v32, v26, v21
	v_mfma_f32_16x16x32_f16 v[144:147], v[128:131], v[50:53], 0
	ds_read_b128 v[166:169], v32 offset:34816
	ds_read_b128 v[188:191], v32 offset:36864
	v_mfma_f32_16x16x32_f16 v[128:131], v[128:131], v[108:111], 0
	ds_read_b128 v[192:195], v32 offset:38912
	s_waitcnt vmcnt(7)
	ds_write_b128 v18, v[54:57] offset:16384
	v_mfma_f32_16x16x32_f16 v[38:41], v[132:135], v[38:41], 0
	s_waitcnt vmcnt(5)
	ds_write_b128 v19, v[62:65] offset:16384
	v_mfma_f32_16x16x32_f16 v[50:53], v[132:135], v[50:53], 0
	s_waitcnt vmcnt(4)
	ds_write_b128 v20, v[66:69] offset:16384
	v_mfma_f32_16x16x32_f16 v[108:111], v[132:135], v[108:111], 0
	ds_read_b128 v[132:135], v32 offset:32768
	s_waitcnt lgkmcnt(6)
	v_mfma_f32_16x16x32_f16 v[46:49], v[158:161], v[166:169], v[46:49]
	s_waitcnt vmcnt(3)
	ds_write_b128 v17, v[70:73] offset:16384
	s_waitcnt lgkmcnt(6)
; #define GL_LOAD(s_, kt_) if (VAR != 1) { a##s_##0 = GL_A(0, kt_); a##s_##1 = GL_A(1, kt_); a##s_##2 = GL_A(2, kt_); a##s_##3 = GL_A(3, kt_); b##s_##0 = GL_B(0, kt_); b##s_##1 = GL_B(1, kt_); b##s_##2 = GL_B(2, kt_); b##s_##3 = GL_B(3, kt_); }
; #define LDS_STORE(s_, buf_) if (VAR != 2) { LDS_ST1(sA, 0, buf_, a##s_##0) LDS_ST1(sA, 1, buf_, a##s_##1) LDS_ST1(sA, 2, buf_, a##s_##2) LDS_ST1(sA, 3, buf_, a##s_##3) LDS_ST1(sB, 0, buf_, b##s_##0) LDS_ST1(sB, 1, buf_, b##s_##1) LDS_ST1(sB, 2, buf_, b##s_##2) LDS_ST1(sB, 3, buf_, b##s_##3) }
;     ...
;   for (int kt = 0; kt < nk; kt += 2) {
;     if (kt + 2 < nk) { GL_LOAD(0, kt + 2) }
;     MMA_TILE(0)
;     LDS_STORE(1, 1)
;     if (VAR != 4) __syncthreads();
;     if (kt + 3 < nk) { GL_LOAD(1, kt + 3) }
;     MMA_TILE(1)
;     if (kt + 2 < nk) { LDS_STORE(0, 0) }
;     if (VAR != 4) __syncthreads();
	v_mfma_f32_16x16x32_f16 v[112:115], v[158:161], v[188:191], v[112:115]
	ds_write_b128 v18, v[58:61] offset:49152
	s_waitcnt lgkmcnt(6)
	v_mfma_f32_16x16x32_f16 v[22:25], v[158:161], v[192:195], v[22:25]
	s_waitcnt vmcnt(2)
	ds_write_b128 v19, v[74:77] offset:49152
	v_mfma_f32_16x16x32_f16 v[120:123], v[162:165], v[166:169], v[120:123]
	s_waitcnt vmcnt(1)
	ds_write_b128 v20, v[78:81] offset:49152
	v_mfma_f32_16x16x32_f16 v[124:127], v[162:165], v[188:191], v[124:127]
	s_waitcnt vmcnt(0)
	ds_write_b128 v17, v[104:107] offset:49152
	v_mfma_f32_16x16x32_f16 v[34:37], v[162:165], v[192:195], v[34:37]
	s_waitcnt lgkmcnt(5)
	v_mfma_f32_16x16x32_f16 v[42:45], v[158:161], v[132:135], v[42:45]
	ds_read_b128 v[158:161], v29 offset:4096
	v_mfma_f32_16x16x32_f16 v[116:119], v[162:165], v[132:135], v[116:119]
	ds_read_b128 v[162:165], v29 offset:6144
	s_waitcnt lgkmcnt(1)
	v_mfma_f32_16x16x32_f16 v[136:139], v[158:161], v[132:135], v[136:139]
	v_mfma_f32_16x16x32_f16 v[140:143], v[158:161], v[166:169], v[140:143]
	s_waitcnt lgkmcnt(0)
	v_mfma_f32_16x16x32_f16 v[132:135], v[162:165], v[132:135], v[154:157]
	s_nop 2
	global_load_dwordx4 v[154:157], v[0:1], off offset:256
	v_mfma_f32_16x16x32_f16 v[38:41], v[162:165], v[166:169], v[38:41]
	v_mfma_f32_16x16x32_f16 v[144:147], v[158:161], v[188:191], v[144:147]
	v_mfma_f32_16x16x32_f16 v[128:131], v[158:161], v[192:195], v[128:131]
	global_load_dwordx4 v[158:161], v[2:3], off offset:256
	global_load_dwordx4 v[196:199], v[4:5], off offset:256
	global_load_dwordx4 v[200:203], v[8:9], off offset:256
	global_load_dwordx4 v[166:169], v[6:7], off offset:256
	global_load_dwordx4 v[204:207], v[10:11], off offset:256
	global_load_dwordx4 v[208:211], v[12:13], off offset:256
	global_load_dwordx4 v[212:215], v[14:15], off offset:256
	s_waitcnt lgkmcnt(0)
	s_barrier
	v_mfma_f32_16x16x32_f16 v[58:61], v[162:165], v[192:195], v[108:111]
	ds_read_b128 v[54:57], v16 offset:16384
	v_mfma_f32_16x16x32_f16 v[50:53], v[162:165], v[188:191], v[50:53]
	ds_read_b128 v[62:65], v28 offset:49152
	s_waitcnt lgkmcnt(0)
	v_mfma_f32_16x16x32_f16 v[42:45], v[54:57], v[62:65], v[42:45]
	ds_read_b128 v[66:69], v16 offset:18432
	ds_read_b128 v[70:73], v28 offset:51200
	s_waitcnt lgkmcnt(0)
	v_mfma_f32_16x16x32_f16 v[46:49], v[54:57], v[70:73], v[46:49]
	ds_read_b128 v[74:77], v28 offset:53248
	s_waitcnt lgkmcnt(0)
	v_mfma_f32_16x16x32_f16 v[104:107], v[54:57], v[74:77], v[112:115]
	ds_read_b128 v[78:81], v28 offset:55296
	s_waitcnt lgkmcnt(0)
	v_mfma_f32_16x16x32_f16 v[22:25], v[54:57], v[78:81], v[22:25]
	v_mfma_f32_16x16x32_f16 v[54:57], v[66:69], v[62:65], v[116:119]
	s_nop 2
	ds_read_b128 v[116:119], v16 offset:22528
	v_mfma_f32_16x16x32_f16 v[108:111], v[66:69], v[70:73], v[120:123]
	s_waitcnt vmcnt(7)
	ds_write_b128 v18, v[154:157]
	s_waitcnt vmcnt(6)
	ds_write_b128 v19, v[158:161]
	s_waitcnt vmcnt(5)
	ds_write_b128 v20, v[196:199]
	v_mfma_f32_16x16x32_f16 v[112:115], v[66:69], v[74:77], v[124:127]
	s_waitcnt vmcnt(4)
	ds_write_b128 v17, v[200:203]
	v_mfma_f32_16x16x32_f16 v[34:37], v[66:69], v[78:81], v[34:37]
	ds_read_b128 v[66:69], v16 offset:20480
	s_waitcnt lgkmcnt(0)
	v_mfma_f32_16x16x32_f16 v[124:127], v[66:69], v[70:73], v[140:143]
	s_waitcnt vmcnt(3)
	ds_write_b128 v18, v[166:169] offset:32768
	v_mfma_f32_16x16x32_f16 v[120:123], v[66:69], v[62:65], v[136:139]
	s_waitcnt vmcnt(2)
	ds_write_b128 v19, v[204:207] offset:32768
	v_mfma_f32_16x16x32_f16 v[38:41], v[116:119], v[70:73], v[38:41]
	ds_read_b128 v[70:73], v29 offset:16384
	v_mfma_f32_16x16x32_f16 v[62:65], v[116:119], v[62:65], v[132:135]
	s_nop 2
	ds_read_b128 v[132:135], v32 offset:55296
	v_mfma_f32_16x16x32_f16 v[136:139], v[66:69], v[74:77], v[144:147]
	s_waitcnt vmcnt(1)
	ds_write_b128 v20, v[208:211] offset:32768
	v_mfma_f32_16x16x32_f16 v[66:69], v[66:69], v[78:81], v[128:131]
	s_nop 2
	ds_read_b128 v[128:131], v32 offset:53248
	v_mfma_f32_16x16x32_f16 v[50:53], v[116:119], v[74:77], v[50:53]
	ds_read_b128 v[74:77], v32 offset:49152
	v_mfma_f32_16x16x32_f16 v[58:61], v[116:119], v[78:81], v[58:61]
	ds_read_b128 v[78:81], v29 offset:18432
	s_waitcnt lgkmcnt(1)
	v_mfma_f32_16x16x32_f16 v[42:45], v[70:73], v[74:77], v[42:45]
	ds_read_b128 v[116:119], v32 offset:51200
	s_waitcnt lgkmcnt(0)
	v_mfma_f32_16x16x32_f16 v[46:49], v[70:73], v[116:119], v[46:49]
	s_waitcnt vmcnt(0)
	ds_write_b128 v17, v[212:215] offset:32768
	v_mfma_f32_16x16x32_f16 v[54:57], v[78:81], v[74:77], v[54:57]
	v_mfma_f32_16x16x32_f16 v[104:107], v[70:73], v[128:131], v[104:107]
	v_mfma_f32_16x16x32_f16 v[22:25], v[70:73], v[132:135], v[22:25]
	v_mfma_f32_16x16x32_f16 v[70:73], v[78:81], v[116:119], v[108:111]
	v_mfma_f32_16x16x32_f16 v[108:111], v[78:81], v[128:131], v[112:115]
	s_nop 2
	ds_read_b128 v[112:115], v29 offset:22528
	v_mfma_f32_16x16x32_f16 v[34:37], v[78:81], v[132:135], v[34:37]
	ds_read_b128 v[78:81], v29 offset:20480
	s_waitcnt lgkmcnt(0)
	v_mfma_f32_16x16x32_f16 v[120:123], v[78:81], v[74:77], v[120:123]
	v_mfma_f32_16x16x32_f16 v[124:127], v[78:81], v[116:119], v[124:127]
	v_mfma_f32_16x16x32_f16 v[62:65], v[112:115], v[74:77], v[62:65]
	global_load_dwordx4 v[74:77], v[0:1], off offset:384
	v_mfma_f32_16x16x32_f16 v[38:41], v[112:115], v[116:119], v[38:41]
	v_mfma_f32_16x16x32_f16 v[136:139], v[78:81], v[128:131], v[136:139]
	v_mfma_f32_16x16x32_f16 v[66:69], v[78:81], v[132:135], v[66:69]
	global_load_dwordx4 v[78:81], v[2:3], off offset:384
	global_load_dwordx4 v[140:143], v[4:5], off offset:384
	v_mfma_f32_16x16x32_f16 v[50:53], v[112:115], v[128:131], v[50:53]
	global_load_dwordx4 v[144:147], v[8:9], off offset:384
	global_load_dwordx4 v[116:119], v[6:7], off offset:384
	global_load_dwordx4 v[162:165], v[10:11], off offset:384
	global_load_dwordx4 v[188:191], v[12:13], off offset:384
	global_load_dwordx4 v[192:195], v[14:15], off offset:384
	s_waitcnt lgkmcnt(0)
	s_barrier
; #define GL_LOAD(s_, kt_) if (VAR != 1) { a##s_##0 = GL_A(0, kt_); a##s_##1 = GL_A(1, kt_); a##s_##2 = GL_A(2, kt_); a##s_##3 = GL_A(3, kt_); b##s_##0 = GL_B(0, kt_); b##s_##1 = GL_B(1, kt_); b##s_##2 = GL_B(2, kt_); b##s_##3 = GL_B(3, kt_); }
; #define LDS_STORE(s_, buf_) if (VAR != 2) { LDS_ST1(sA, 0, buf_, a##s_##0) LDS_ST1(sA, 1, buf_, a##s_##1) LDS_ST1(sA, 2, buf_, a##s_##2) LDS_ST1(sA, 3, buf_, a##s_##3) LDS_ST1(sB, 0, buf_, b##s_##0) LDS_ST1(sB, 1, buf_, b##s_##1) LDS_ST1(sB, 2, buf_, b##s_##2) LDS_ST1(sB, 3, buf_, b##s_##3) }
;     ...
;   for (int kt = 0; kt < nk; kt += 2) {
;     if (kt + 2 < nk) { GL_LOAD(0, kt + 2) }
;     MMA_TILE(0)
;     LDS_STORE(1, 1)
;     if (VAR != 4) __syncthreads();
;     if (kt + 3 < nk) { GL_LOAD(1, kt + 3) }
;     MMA_TILE(1)
;     if (kt + 2 < nk) { LDS_STORE(0, 0) }
;     if (VAR != 4) __syncthreads();
	v_mfma_f32_16x16x32_f16 v[58:61], v[112:115], v[132:135], v[58:61]
	ds_read_b128 v[128:131], v16
	ds_read_b128 v[112:115], v28 offset:32768
	s_waitcnt lgkmcnt(0)
	v_mfma_f32_16x16x32_f16 v[42:45], v[128:131], v[112:115], v[42:45]
	ds_read_b128 v[132:135], v16 offset:2048
	ds_read_b128 v[154:157], v28 offset:34816
	s_waitcnt lgkmcnt(0)
	v_mfma_f32_16x16x32_f16 v[46:49], v[128:131], v[154:157], v[46:49]
	ds_read_b128 v[158:161], v28 offset:36864
	v_mfma_f32_16x16x32_f16 v[54:57], v[132:135], v[112:115], v[54:57]
	ds_read_b128 v[166:169], v28 offset:38912
	v_mfma_f32_16x16x32_f16 v[70:73], v[132:135], v[154:157], v[70:73]
	s_waitcnt vmcnt(7)
	ds_write_b128 v18, v[74:77] offset:16384
	s_waitcnt lgkmcnt(2)
	v_mfma_f32_16x16x32_f16 v[104:107], v[128:131], v[158:161], v[104:107]
	s_waitcnt vmcnt(6)
	ds_write_b128 v19, v[78:81] offset:16384
	s_waitcnt lgkmcnt(2)
	v_mfma_f32_16x16x32_f16 v[22:25], v[128:131], v[166:169], v[22:25]
	ds_read_b128 v[128:131], v16 offset:4096
	v_mfma_f32_16x16x32_f16 v[108:111], v[132:135], v[158:161], v[108:111]
	s_waitcnt vmcnt(5)
	ds_write_b128 v20, v[140:143] offset:16384
	v_mfma_f32_16x16x32_f16 v[34:37], v[132:135], v[166:169], v[34:37]
	ds_read_b128 v[132:135], v16 offset:6144
	s_waitcnt lgkmcnt(2)
	v_mfma_f32_16x16x32_f16 v[120:123], v[128:131], v[112:115], v[120:123]
	s_waitcnt vmcnt(4)
	ds_write_b128 v17, v[144:147] offset:16384
	v_mfma_f32_16x16x32_f16 v[124:127], v[128:131], v[154:157], v[124:127]
	s_waitcnt vmcnt(3)
	ds_write_b128 v18, v[116:119] offset:49152
	s_waitcnt lgkmcnt(2)
	v_mfma_f32_16x16x32_f16 v[62:65], v[132:135], v[112:115], v[62:65]
	ds_read_b128 v[112:115], v29
	v_mfma_f32_16x16x32_f16 v[38:41], v[132:135], v[154:157], v[38:41]
	ds_read_b128 v[154:157], v32 offset:34816
	v_mfma_f32_16x16x32_f16 v[136:139], v[128:131], v[158:161], v[136:139]
	s_waitcnt vmcnt(2)
	ds_write_b128 v19, v[162:165] offset:49152
	v_mfma_f32_16x16x32_f16 v[66:69], v[128:131], v[166:169], v[66:69]
	ds_read_b128 v[128:131], v32 offset:32768
	v_mfma_f32_16x16x32_f16 v[50:53], v[132:135], v[158:161], v[50:53]
	ds_read_b128 v[158:161], v32 offset:36864
	v_mfma_f32_16x16x32_f16 v[58:61], v[132:135], v[166:169], v[58:61]
	ds_read_b128 v[132:135], v29 offset:2048
	s_waitcnt lgkmcnt(2)
	v_mfma_f32_16x16x32_f16 v[42:45], v[112:115], v[128:131], v[42:45]
	ds_read_b128 v[166:169], v32 offset:38912
	v_mfma_f32_16x16x32_f16 v[46:49], v[112:115], v[154:157], v[46:49]
	s_waitcnt vmcnt(1)
	ds_write_b128 v20, v[188:191] offset:49152
	s_waitcnt lgkmcnt(2)
	v_mfma_f32_16x16x32_f16 v[54:57], v[132:135], v[128:131], v[54:57]
	s_waitcnt vmcnt(0)
	ds_write_b128 v17, v[192:195] offset:49152
	v_mfma_f32_16x16x32_f16 v[70:73], v[132:135], v[154:157], v[70:73]
	v_mfma_f32_16x16x32_f16 v[104:107], v[112:115], v[158:161], v[104:107]
	s_waitcnt lgkmcnt(2)
	v_mfma_f32_16x16x32_f16 v[22:25], v[112:115], v[166:169], v[22:25]
	ds_read_b128 v[112:115], v29 offset:4096
	v_mfma_f32_16x16x32_f16 v[108:111], v[132:135], v[158:161], v[108:111]
	v_mfma_f32_16x16x32_f16 v[34:37], v[132:135], v[166:169], v[34:37]
	ds_read_b128 v[132:135], v29 offset:6144
	s_waitcnt lgkmcnt(1)
	v_mfma_f32_16x16x32_f16 v[120:123], v[112:115], v[128:131], v[120:123]
	v_mfma_f32_16x16x32_f16 v[124:127], v[112:115], v[154:157], v[124:127]
	s_waitcnt lgkmcnt(0)
	v_mfma_f32_16x16x32_f16 v[62:65], v[132:135], v[128:131], v[62:65]
	v_mfma_f32_16x16x32_f16 v[38:41], v[132:135], v[154:157], v[38:41]
	v_mfma_f32_16x16x32_f16 v[136:139], v[112:115], v[158:161], v[136:139]
	v_mfma_f32_16x16x32_f16 v[66:69], v[112:115], v[166:169], v[66:69]
	global_load_dwordx4 v[112:115], v[0:1], off offset:512
	global_load_dwordx4 v[128:131], v[2:3], off offset:512
	global_load_dwordx4 v[196:199], v[4:5], off offset:512
	global_load_dwordx4 v[200:203], v[8:9], off offset:512
	global_load_dwordx4 v[154:157], v[6:7], off offset:512
	global_load_dwordx4 v[204:207], v[10:11], off offset:512
	global_load_dwordx4 v[208:211], v[12:13], off offset:512
	global_load_dwordx4 v[212:215], v[14:15], off offset:512
	s_waitcnt lgkmcnt(0)
	s_barrier
	v_mfma_f32_16x16x32_f16 v[50:53], v[132:135], v[158:161], v[50:53]
	ds_read_b128 v[74:77], v16 offset:16384
	v_mfma_f32_16x16x32_f16 v[58:61], v[132:135], v[166:169], v[58:61]
	ds_read_b128 v[78:81], v28 offset:49152
	s_waitcnt lgkmcnt(0)
	v_mfma_f32_16x16x32_f16 v[42:45], v[74:77], v[78:81], v[42:45]
	ds_read_b128 v[116:119], v16 offset:18432
	ds_read_b128 v[132:135], v28 offset:51200
	s_waitcnt lgkmcnt(0)
	v_mfma_f32_16x16x32_f16 v[46:49], v[74:77], v[132:135], v[46:49]
	ds_read_b128 v[140:143], v28 offset:53248
	v_mfma_f32_16x16x32_f16 v[54:57], v[116:119], v[78:81], v[54:57]
	ds_read_b128 v[144:147], v28 offset:55296
	v_mfma_f32_16x16x32_f16 v[70:73], v[116:119], v[132:135], v[70:73]
	s_waitcnt vmcnt(7)
	ds_write_b128 v18, v[112:115]
	s_waitcnt lgkmcnt(2)
	v_mfma_f32_16x16x32_f16 v[104:107], v[74:77], v[140:143], v[104:107]
	s_waitcnt vmcnt(6)
	ds_write_b128 v19, v[128:131]
	s_waitcnt lgkmcnt(2)
	v_mfma_f32_16x16x32_f16 v[22:25], v[74:77], v[144:147], v[22:25]
	s_waitcnt vmcnt(5)
	ds_write_b128 v20, v[196:199]
	v_mfma_f32_16x16x32_f16 v[74:77], v[116:119], v[140:143], v[108:111]
	s_nop 2
	ds_read_b128 v[108:111], v16 offset:20480
	v_mfma_f32_16x16x32_f16 v[34:37], v[116:119], v[144:147], v[34:37]
	ds_read_b128 v[116:119], v16 offset:22528
	s_waitcnt lgkmcnt(1)
	v_mfma_f32_16x16x32_f16 v[120:123], v[108:111], v[78:81], v[120:123]
	s_waitcnt vmcnt(4)
	ds_write_b128 v17, v[200:203]
	v_mfma_f32_16x16x32_f16 v[124:127], v[108:111], v[132:135], v[124:127]
	s_waitcnt vmcnt(3)
	ds_write_b128 v18, v[154:157] offset:32768
	s_waitcnt lgkmcnt(2)
; #define GL_LOAD(s_, kt_) if (VAR != 1) { a##s_##0 = GL_A(0, kt_); a##s_##1 = GL_A(1, kt_); a##s_##2 = GL_A(2, kt_); a##s_##3 = GL_A(3, kt_); b##s_##0 = GL_B(0, kt_); b##s_##1 = GL_B(1, kt_); b##s_##2 = GL_B(2, kt_); b##s_##3 = GL_B(3, kt_); }
; #define LDS_STORE(s_, buf_) if (VAR != 2) { LDS_ST1(sA, 0, buf_, a##s_##0) LDS_ST1(sA, 1, buf_, a##s_##1) LDS_ST1(sA, 2, buf_, a##s_##2) LDS_ST1(sA, 3, buf_, a##s_##3) LDS_ST1(sB, 0, buf_, b##s_##0) LDS_ST1(sB, 1, buf_, b##s_##1) LDS_ST1(sB, 2, buf_, b##s_##2) LDS_ST1(sB, 3, buf_, b##s_##3) }
;     ...
;   GL_LOAD(0, 0)
;   GL_LOAD(1, 1)
;   LDS_STORE(0, 0)
;   if (VAR != 4) __syncthreads();
; #pragma unroll
;   for (int kt = 0; kt < nk; kt += 2) {
;     if (kt + 2 < nk) { GL_LOAD(0, kt + 2) }
;     MMA_TILE(0)
;     LDS_STORE(1, 1)
;     if (VAR != 4) __syncthreads();
;     if (kt + 3 < nk) { GL_LOAD(1, kt + 3) }
;     MMA_TILE(1)
;     if (kt + 2 < nk) { LDS_STORE(0, 0) }
;     if (VAR != 4) __syncthreads();
	v_mfma_f32_16x16x32_f16 v[62:65], v[116:119], v[78:81], v[62:65]
	ds_read_b128 v[78:81], v29 offset:16384
	v_mfma_f32_16x16x32_f16 v[38:41], v[116:119], v[132:135], v[38:41]
	ds_read_b128 v[132:135], v32 offset:51200
	v_mfma_f32_16x16x32_f16 v[136:139], v[108:111], v[140:143], v[136:139]
	s_waitcnt vmcnt(2)
	ds_write_b128 v19, v[204:207] offset:32768
	v_mfma_f32_16x16x32_f16 v[66:69], v[108:111], v[144:147], v[66:69]
	ds_read_b128 v[108:111], v32 offset:49152
	v_mfma_f32_16x16x32_f16 v[50:53], v[116:119], v[140:143], v[50:53]
	ds_read_b128 v[140:143], v32 offset:53248
	v_mfma_f32_16x16x32_f16 v[58:61], v[116:119], v[144:147], v[58:61]
	ds_read_b128 v[116:119], v29 offset:18432
	s_waitcnt lgkmcnt(2)
	v_mfma_f32_16x16x32_f16 v[42:45], v[78:81], v[108:111], v[42:45]
	ds_read_b128 v[144:147], v32 offset:55296
	v_mfma_f32_16x16x32_f16 v[46:49], v[78:81], v[132:135], v[46:49]
	s_waitcnt vmcnt(1)
	ds_write_b128 v20, v[208:211] offset:32768
	s_waitcnt lgkmcnt(2)
	v_mfma_f32_16x16x32_f16 v[54:57], v[116:119], v[108:111], v[54:57]
	s_waitcnt vmcnt(0)
	ds_write_b128 v17, v[212:215] offset:32768
	v_mfma_f32_16x16x32_f16 v[70:73], v[116:119], v[132:135], v[70:73]
	v_mfma_f32_16x16x32_f16 v[104:107], v[78:81], v[140:143], v[104:107]
	s_waitcnt lgkmcnt(2)
	v_mfma_f32_16x16x32_f16 v[22:25], v[78:81], v[144:147], v[22:25]
	ds_read_b128 v[78:81], v29 offset:20480
	v_mfma_f32_16x16x32_f16 v[74:77], v[116:119], v[140:143], v[74:77]
	v_mfma_f32_16x16x32_f16 v[34:37], v[116:119], v[144:147], v[34:37]
	ds_read_b128 v[116:119], v29 offset:22528
	s_waitcnt lgkmcnt(1)
	v_mfma_f32_16x16x32_f16 v[120:123], v[78:81], v[108:111], v[120:123]
	v_mfma_f32_16x16x32_f16 v[124:127], v[78:81], v[132:135], v[124:127]
	s_waitcnt lgkmcnt(0)
	v_mfma_f32_16x16x32_f16 v[62:65], v[116:119], v[108:111], v[62:65]
	v_mfma_f32_16x16x32_f16 v[38:41], v[116:119], v[132:135], v[38:41]
	v_mfma_f32_16x16x32_f16 v[136:139], v[78:81], v[140:143], v[136:139]
	v_mfma_f32_16x16x32_f16 v[66:69], v[78:81], v[144:147], v[66:69]
	global_load_dwordx4 v[78:81], v[0:1], off offset:640
	global_load_dwordx4 v[108:111], v[2:3], off offset:640
	global_load_dwordx4 v[158:161], v[4:5], off offset:640
	global_load_dwordx4 v[162:165], v[8:9], off offset:640
	global_load_dwordx4 v[132:135], v[6:7], off offset:640
	global_load_dwordx4 v[166:169], v[10:11], off offset:640
	global_load_dwordx4 v[188:191], v[12:13], off offset:640
	global_load_dwordx4 v[192:195], v[14:15], off offset:640
	s_waitcnt lgkmcnt(0)
	s_barrier
	v_mfma_f32_16x16x32_f16 v[50:53], v[116:119], v[140:143], v[50:53]
	ds_read_b128 v[112:115], v16
	v_mfma_f32_16x16x32_f16 v[58:61], v[116:119], v[144:147], v[58:61]
	ds_read_b128 v[116:119], v28 offset:32768
	s_waitcnt lgkmcnt(0)
	v_mfma_f32_16x16x32_f16 v[42:45], v[112:115], v[116:119], v[42:45]
	ds_read_b128 v[128:131], v16 offset:2048
	ds_read_b128 v[140:143], v28 offset:34816
	s_waitcnt lgkmcnt(0)
	v_mfma_f32_16x16x32_f16 v[46:49], v[112:115], v[140:143], v[46:49]
	ds_read_b128 v[144:147], v28 offset:36864
	v_mfma_f32_16x16x32_f16 v[54:57], v[128:131], v[116:119], v[54:57]
	ds_read_b128 v[154:157], v28 offset:38912
	v_mfma_f32_16x16x32_f16 v[70:73], v[128:131], v[140:143], v[70:73]
	s_waitcnt vmcnt(7)
	ds_write_b128 v18, v[78:81] offset:16384
	s_waitcnt lgkmcnt(2)
	v_mfma_f32_16x16x32_f16 v[104:107], v[112:115], v[144:147], v[104:107]
	s_waitcnt vmcnt(6)
	ds_write_b128 v19, v[108:111] offset:16384
	s_waitcnt lgkmcnt(2)
	v_mfma_f32_16x16x32_f16 v[22:25], v[112:115], v[154:157], v[22:25]
	ds_read_b128 v[112:115], v16 offset:4096
	v_mfma_f32_16x16x32_f16 v[74:77], v[128:131], v[144:147], v[74:77]
	s_waitcnt vmcnt(5)
	ds_write_b128 v20, v[158:161] offset:16384
	v_mfma_f32_16x16x32_f16 v[34:37], v[128:131], v[154:157], v[34:37]
	ds_read_b128 v[128:131], v16 offset:6144
	s_waitcnt lgkmcnt(2)
	v_mfma_f32_16x16x32_f16 v[120:123], v[112:115], v[116:119], v[120:123]
	s_waitcnt vmcnt(4)
	ds_write_b128 v17, v[162:165] offset:16384
	v_mfma_f32_16x16x32_f16 v[124:127], v[112:115], v[140:143], v[124:127]
	s_waitcnt vmcnt(3)
	ds_write_b128 v18, v[132:135] offset:49152
	s_waitcnt lgkmcnt(2)
	v_mfma_f32_16x16x32_f16 v[62:65], v[128:131], v[116:119], v[62:65]
	ds_read_b128 v[116:119], v32 offset:32768
	v_mfma_f32_16x16x32_f16 v[38:41], v[128:131], v[140:143], v[38:41]
	ds_read_b128 v[140:143], v32 offset:34816
	v_mfma_f32_16x16x32_f16 v[136:139], v[112:115], v[144:147], v[136:139]
	s_waitcnt vmcnt(2)
	ds_write_b128 v19, v[166:169] offset:49152
	v_mfma_f32_16x16x32_f16 v[66:69], v[112:115], v[154:157], v[66:69]
	ds_read_b128 v[112:115], v29
	v_mfma_f32_16x16x32_f16 v[50:53], v[128:131], v[144:147], v[50:53]
	ds_read_b128 v[144:147], v32 offset:36864
	v_mfma_f32_16x16x32_f16 v[58:61], v[128:131], v[154:157], v[58:61]
	ds_read_b128 v[128:131], v29 offset:2048
	s_waitcnt lgkmcnt(2)
	v_mfma_f32_16x16x32_f16 v[42:45], v[112:115], v[116:119], v[42:45]
	ds_read_b128 v[154:157], v32 offset:38912
	v_mfma_f32_16x16x32_f16 v[46:49], v[112:115], v[140:143], v[46:49]
	s_waitcnt vmcnt(1)
	ds_write_b128 v20, v[188:191] offset:49152
	s_waitcnt lgkmcnt(2)
	v_mfma_f32_16x16x32_f16 v[54:57], v[128:131], v[116:119], v[54:57]
	s_waitcnt vmcnt(0)
	ds_write_b128 v17, v[192:195] offset:49152
	v_mfma_f32_16x16x32_f16 v[70:73], v[128:131], v[140:143], v[70:73]
	v_mfma_f32_16x16x32_f16 v[104:107], v[112:115], v[144:147], v[104:107]
	s_waitcnt lgkmcnt(2)
	v_mfma_f32_16x16x32_f16 v[22:25], v[112:115], v[154:157], v[22:25]
	ds_read_b128 v[112:115], v29 offset:4096
	v_mfma_f32_16x16x32_f16 v[74:77], v[128:131], v[144:147], v[74:77]
	v_mfma_f32_16x16x32_f16 v[34:37], v[128:131], v[154:157], v[34:37]
	ds_read_b128 v[128:131], v29 offset:6144
	s_waitcnt lgkmcnt(1)
	v_mfma_f32_16x16x32_f16 v[120:123], v[112:115], v[116:119], v[120:123]
	v_mfma_f32_16x16x32_f16 v[124:127], v[112:115], v[140:143], v[124:127]
	s_waitcnt lgkmcnt(0)
	v_mfma_f32_16x16x32_f16 v[62:65], v[128:131], v[116:119], v[62:65]
	v_mfma_f32_16x16x32_f16 v[38:41], v[128:131], v[140:143], v[38:41]
	v_mfma_f32_16x16x32_f16 v[136:139], v[112:115], v[144:147], v[136:139]
	v_mfma_f32_16x16x32_f16 v[66:69], v[112:115], v[154:157], v[66:69]
	global_load_dwordx4 v[112:115], v[0:1], off offset:768
	global_load_dwordx4 v[116:119], v[2:3], off offset:768
	global_load_dwordx4 v[196:199], v[4:5], off offset:768
	global_load_dwordx4 v[200:203], v[8:9], off offset:768
	global_load_dwordx4 v[140:143], v[6:7], off offset:768
	global_load_dwordx4 v[204:207], v[10:11], off offset:768
	global_load_dwordx4 v[208:211], v[12:13], off offset:768
	global_load_dwordx4 v[212:215], v[14:15], off offset:768
	s_waitcnt lgkmcnt(0)
	s_barrier
; #define GL_LOAD(s_, kt_) if (VAR != 1) { a##s_##0 = GL_A(0, kt_); a##s_##1 = GL_A(1, kt_); a##s_##2 = GL_A(2, kt_); a##s_##3 = GL_A(3, kt_); b##s_##0 = GL_B(0, kt_); b##s_##1 = GL_B(1, kt_); b##s_##2 = GL_B(2, kt_); b##s_##3 = GL_B(3, kt_); }
; #define LDS_STORE(s_, buf_) if (VAR != 2) { LDS_ST1(sA, 0, buf_, a##s_##0) LDS_ST1(sA, 1, buf_, a##s_##1) LDS_ST1(sA, 2, buf_, a##s_##2) LDS_ST1(sA, 3, buf_, a##s_##3) LDS_ST1(sB, 0, buf_, b##s_##0) LDS_ST1(sB, 1, buf_, b##s_##1) LDS_ST1(sB, 2, buf_, b##s_##2) LDS_ST1(sB, 3, buf_, b##s_##3) }
;     ...
;   GL_LOAD(0, 0)
;   GL_LOAD(1, 1)
;   LDS_STORE(0, 0)
;   if (VAR != 4) __syncthreads();
; #pragma unroll
;   for (int kt = 0; kt < nk; kt += 2) {
;     if (kt + 2 < nk) { GL_LOAD(0, kt + 2) }
;     MMA_TILE(0)
;     LDS_STORE(1, 1)
;     if (VAR != 4) __syncthreads();
;     if (kt + 3 < nk) { GL_LOAD(1, kt + 3) }
;     MMA_TILE(1)
;     if (kt + 2 < nk) { LDS_STORE(0, 0) }
;     if (VAR != 4) __syncthreads();
	v_mfma_f32_16x16x32_f16 v[50:53], v[128:131], v[144:147], v[50:53]
	ds_read_b128 v[78:81], v16 offset:16384
	v_mfma_f32_16x16x32_f16 v[58:61], v[128:131], v[154:157], v[58:61]
	ds_read_b128 v[108:111], v28 offset:49152
	s_waitcnt lgkmcnt(0)
	v_mfma_f32_16x16x32_f16 v[42:45], v[78:81], v[108:111], v[42:45]
	ds_read_b128 v[128:131], v16 offset:18432
	ds_read_b128 v[132:135], v28 offset:51200
	s_waitcnt lgkmcnt(0)
	v_mfma_f32_16x16x32_f16 v[46:49], v[78:81], v[132:135], v[46:49]
	ds_read_b128 v[144:147], v28 offset:53248
	v_mfma_f32_16x16x32_f16 v[54:57], v[128:131], v[108:111], v[54:57]
	ds_read_b128 v[154:157], v28 offset:55296
	v_mfma_f32_16x16x32_f16 v[70:73], v[128:131], v[132:135], v[70:73]
	s_waitcnt vmcnt(7)
	ds_write_b128 v18, v[112:115]
	s_waitcnt lgkmcnt(2)
	v_mfma_f32_16x16x32_f16 v[104:107], v[78:81], v[144:147], v[104:107]
	s_waitcnt vmcnt(6)
	ds_write_b128 v19, v[116:119]
	s_waitcnt lgkmcnt(2)
	v_mfma_f32_16x16x32_f16 v[22:25], v[78:81], v[154:157], v[22:25]
	ds_read_b128 v[78:81], v16 offset:20480
	v_mfma_f32_16x16x32_f16 v[74:77], v[128:131], v[144:147], v[74:77]
	s_waitcnt vmcnt(5)
	ds_write_b128 v20, v[196:199]
	v_mfma_f32_16x16x32_f16 v[34:37], v[128:131], v[154:157], v[34:37]
	ds_read_b128 v[128:131], v16 offset:22528
	s_waitcnt lgkmcnt(2)
	v_mfma_f32_16x16x32_f16 v[120:123], v[78:81], v[108:111], v[120:123]
	s_waitcnt vmcnt(4)
	ds_write_b128 v17, v[200:203]
	v_mfma_f32_16x16x32_f16 v[124:127], v[78:81], v[132:135], v[124:127]
	s_waitcnt vmcnt(3)
	ds_write_b128 v18, v[140:143] offset:32768
	s_waitcnt lgkmcnt(2)
	v_mfma_f32_16x16x32_f16 v[62:65], v[128:131], v[108:111], v[62:65]
	ds_read_b128 v[108:111], v32 offset:49152
	v_mfma_f32_16x16x32_f16 v[38:41], v[128:131], v[132:135], v[38:41]
	ds_read_b128 v[132:135], v32 offset:51200
	v_mfma_f32_16x16x32_f16 v[136:139], v[78:81], v[144:147], v[136:139]
	s_waitcnt vmcnt(2)
	ds_write_b128 v19, v[204:207] offset:32768
	v_mfma_f32_16x16x32_f16 v[66:69], v[78:81], v[154:157], v[66:69]
	ds_read_b128 v[78:81], v29 offset:16384
	v_mfma_f32_16x16x32_f16 v[50:53], v[128:131], v[144:147], v[50:53]
	ds_read_b128 v[144:147], v32 offset:53248
	v_mfma_f32_16x16x32_f16 v[58:61], v[128:131], v[154:157], v[58:61]
	ds_read_b128 v[128:131], v29 offset:18432
	s_waitcnt lgkmcnt(2)
	v_mfma_f32_16x16x32_f16 v[42:45], v[78:81], v[108:111], v[42:45]
	ds_read_b128 v[154:157], v32 offset:55296
	v_mfma_f32_16x16x32_f16 v[46:49], v[78:81], v[132:135], v[46:49]
	s_waitcnt vmcnt(1)
	ds_write_b128 v20, v[208:211] offset:32768
	s_waitcnt lgkmcnt(2)
	v_mfma_f32_16x16x32_f16 v[54:57], v[128:131], v[108:111], v[54:57]
	s_waitcnt vmcnt(0)
	ds_write_b128 v17, v[212:215] offset:32768
	v_mfma_f32_16x16x32_f16 v[70:73], v[128:131], v[132:135], v[70:73]
	v_mfma_f32_16x16x32_f16 v[104:107], v[78:81], v[144:147], v[104:107]
	s_waitcnt lgkmcnt(2)
	v_mfma_f32_16x16x32_f16 v[22:25], v[78:81], v[154:157], v[22:25]
	ds_read_b128 v[78:81], v29 offset:20480
	v_mfma_f32_16x16x32_f16 v[74:77], v[128:131], v[144:147], v[74:77]
	v_mfma_f32_16x16x32_f16 v[34:37], v[128:131], v[154:157], v[34:37]
	ds_read_b128 v[128:131], v29 offset:22528
	s_waitcnt lgkmcnt(1)
	v_mfma_f32_16x16x32_f16 v[120:123], v[78:81], v[108:111], v[120:123]
	v_mfma_f32_16x16x32_f16 v[124:127], v[78:81], v[132:135], v[124:127]
	s_waitcnt lgkmcnt(0)
	v_mfma_f32_16x16x32_f16 v[62:65], v[128:131], v[108:111], v[62:65]
	v_mfma_f32_16x16x32_f16 v[38:41], v[128:131], v[132:135], v[38:41]
	v_mfma_f32_16x16x32_f16 v[136:139], v[78:81], v[144:147], v[136:139]
	v_mfma_f32_16x16x32_f16 v[66:69], v[78:81], v[154:157], v[66:69]
	global_load_dwordx4 v[78:81], v[0:1], off offset:896
	global_load_dwordx4 v[108:111], v[2:3], off offset:896
	global_load_dwordx4 v[158:161], v[4:5], off offset:896
	global_load_dwordx4 v[162:165], v[8:9], off offset:896
	global_load_dwordx4 v[132:135], v[6:7], off offset:896
	global_load_dwordx4 v[166:169], v[10:11], off offset:896
	global_load_dwordx4 v[188:191], v[12:13], off offset:896
	global_load_dwordx4 v[192:195], v[14:15], off offset:896
	s_waitcnt lgkmcnt(0)
	s_barrier
	v_mfma_f32_16x16x32_f16 v[50:53], v[128:131], v[144:147], v[50:53]
	ds_read_b128 v[112:115], v16
	v_mfma_f32_16x16x32_f16 v[58:61], v[128:131], v[154:157], v[58:61]
	ds_read_b128 v[116:119], v28 offset:32768
	s_waitcnt lgkmcnt(0)
	v_mfma_f32_16x16x32_f16 v[42:45], v[112:115], v[116:119], v[42:45]
	ds_read_b128 v[128:131], v16 offset:2048
	ds_read_b128 v[140:143], v28 offset:34816
	s_waitcnt lgkmcnt(0)
	v_mfma_f32_16x16x32_f16 v[46:49], v[112:115], v[140:143], v[46:49]
	ds_read_b128 v[144:147], v28 offset:36864
	v_mfma_f32_16x16x32_f16 v[54:57], v[128:131], v[116:119], v[54:57]
	ds_read_b128 v[154:157], v28 offset:38912
	v_mfma_f32_16x16x32_f16 v[70:73], v[128:131], v[140:143], v[70:73]
	s_waitcnt vmcnt(7)
	ds_write_b128 v18, v[78:81] offset:16384
	s_waitcnt lgkmcnt(2)
	v_mfma_f32_16x16x32_f16 v[104:107], v[112:115], v[144:147], v[104:107]
	s_waitcnt vmcnt(6)
	ds_write_b128 v19, v[108:111] offset:16384
	s_waitcnt lgkmcnt(2)
	v_mfma_f32_16x16x32_f16 v[22:25], v[112:115], v[154:157], v[22:25]
	ds_read_b128 v[112:115], v16 offset:4096
	v_mfma_f32_16x16x32_f16 v[74:77], v[128:131], v[144:147], v[74:77]
	s_waitcnt vmcnt(5)
	ds_write_b128 v20, v[158:161] offset:16384
	v_mfma_f32_16x16x32_f16 v[34:37], v[128:131], v[154:157], v[34:37]
	ds_read_b128 v[128:131], v16 offset:6144
	s_waitcnt lgkmcnt(2)
	v_mfma_f32_16x16x32_f16 v[120:123], v[112:115], v[116:119], v[120:123]
	s_waitcnt vmcnt(4)
	ds_write_b128 v17, v[162:165] offset:16384
	v_mfma_f32_16x16x32_f16 v[124:127], v[112:115], v[140:143], v[124:127]
	s_waitcnt vmcnt(3)
	ds_write_b128 v18, v[132:135] offset:49152
	s_waitcnt lgkmcnt(2)
; #define GL_LOAD(s_, kt_) if (VAR != 1) { a##s_##0 = GL_A(0, kt_); a##s_##1 = GL_A(1, kt_); a##s_##2 = GL_A(2, kt_); a##s_##3 = GL_A(3, kt_); b##s_##0 = GL_B(0, kt_); b##s_##1 = GL_B(1, kt_); b##s_##2 = GL_B(2, kt_); b##s_##3 = GL_B(3, kt_); }
; #define LDS_STORE(s_, buf_) if (VAR != 2) { LDS_ST1(sA, 0, buf_, a##s_##0) LDS_ST1(sA, 1, buf_, a##s_##1) LDS_ST1(sA, 2, buf_, a##s_##2) LDS_ST1(sA, 3, buf_, a##s_##3) LDS_ST1(sB, 0, buf_, b##s_##0) LDS_ST1(sB, 1, buf_, b##s_##1) LDS_ST1(sB, 2, buf_, b##s_##2) LDS_ST1(sB, 3, buf_, b##s_##3) }
;     ...
;   GL_LOAD(0, 0)
;   GL_LOAD(1, 1)
;   LDS_STORE(0, 0)
;   if (VAR != 4) __syncthreads();
; #pragma unroll
;   for (int kt = 0; kt < nk; kt += 2) {
;     if (kt + 2 < nk) { GL_LOAD(0, kt + 2) }
;     MMA_TILE(0)
;     LDS_STORE(1, 1)
;     if (VAR != 4) __syncthreads();
;     if (kt + 3 < nk) { GL_LOAD(1, kt + 3) }
;     MMA_TILE(1)
;     if (kt + 2 < nk) { LDS_STORE(0, 0) }
;     if (VAR != 4) __syncthreads();
	v_mfma_f32_16x16x32_f16 v[62:65], v[128:131], v[116:119], v[62:65]
	ds_read_b128 v[116:119], v32 offset:32768
	v_mfma_f32_16x16x32_f16 v[38:41], v[128:131], v[140:143], v[38:41]
	ds_read_b128 v[140:143], v32 offset:34816
	v_mfma_f32_16x16x32_f16 v[136:139], v[112:115], v[144:147], v[136:139]
	s_waitcnt vmcnt(2)
	ds_write_b128 v19, v[166:169] offset:49152
	v_mfma_f32_16x16x32_f16 v[66:69], v[112:115], v[154:157], v[66:69]
	ds_read_b128 v[112:115], v29
	v_mfma_f32_16x16x32_f16 v[50:53], v[128:131], v[144:147], v[50:53]
	ds_read_b128 v[144:147], v32 offset:36864
	v_mfma_f32_16x16x32_f16 v[58:61], v[128:131], v[154:157], v[58:61]
	ds_read_b128 v[128:131], v29 offset:2048
	s_waitcnt lgkmcnt(2)
	v_mfma_f32_16x16x32_f16 v[42:45], v[112:115], v[116:119], v[42:45]
	ds_read_b128 v[154:157], v32 offset:38912
	v_mfma_f32_16x16x32_f16 v[46:49], v[112:115], v[140:143], v[46:49]
	s_waitcnt vmcnt(1)
	ds_write_b128 v20, v[188:191] offset:49152
	s_waitcnt lgkmcnt(2)
	v_mfma_f32_16x16x32_f16 v[54:57], v[128:131], v[116:119], v[54:57]
	s_waitcnt vmcnt(0)
	ds_write_b128 v17, v[192:195] offset:49152
	v_mfma_f32_16x16x32_f16 v[70:73], v[128:131], v[140:143], v[70:73]
	v_mfma_f32_16x16x32_f16 v[104:107], v[112:115], v[144:147], v[104:107]
	s_waitcnt lgkmcnt(2)
	v_mfma_f32_16x16x32_f16 v[22:25], v[112:115], v[154:157], v[22:25]
	ds_read_b128 v[112:115], v29 offset:4096
	v_mfma_f32_16x16x32_f16 v[74:77], v[128:131], v[144:147], v[74:77]
	v_mfma_f32_16x16x32_f16 v[34:37], v[128:131], v[154:157], v[34:37]
	ds_read_b128 v[128:131], v29 offset:6144
	s_waitcnt lgkmcnt(1)
	v_mfma_f32_16x16x32_f16 v[120:123], v[112:115], v[116:119], v[120:123]
	v_mfma_f32_16x16x32_f16 v[124:127], v[112:115], v[140:143], v[124:127]
	s_waitcnt lgkmcnt(0)
	v_mfma_f32_16x16x32_f16 v[62:65], v[128:131], v[116:119], v[62:65]
	v_mfma_f32_16x16x32_f16 v[38:41], v[128:131], v[140:143], v[38:41]
	v_mfma_f32_16x16x32_f16 v[136:139], v[112:115], v[144:147], v[136:139]
	v_mfma_f32_16x16x32_f16 v[66:69], v[112:115], v[154:157], v[66:69]
	global_load_dwordx4 v[112:115], v[0:1], off offset:1024
	global_load_dwordx4 v[116:119], v[2:3], off offset:1024
	global_load_dwordx4 v[196:199], v[4:5], off offset:1024
	global_load_dwordx4 v[200:203], v[8:9], off offset:1024
	global_load_dwordx4 v[140:143], v[6:7], off offset:1024
	global_load_dwordx4 v[204:207], v[10:11], off offset:1024
	global_load_dwordx4 v[208:211], v[12:13], off offset:1024
	global_load_dwordx4 v[212:215], v[14:15], off offset:1024
	s_waitcnt lgkmcnt(0)
	s_barrier
	v_mfma_f32_16x16x32_f16 v[50:53], v[128:131], v[144:147], v[50:53]
	ds_read_b128 v[78:81], v16 offset:16384
	v_mfma_f32_16x16x32_f16 v[58:61], v[128:131], v[154:157], v[58:61]
	ds_read_b128 v[108:111], v28 offset:49152
	s_waitcnt lgkmcnt(0)
	v_mfma_f32_16x16x32_f16 v[42:45], v[78:81], v[108:111], v[42:45]
	ds_read_b128 v[128:131], v16 offset:18432
	ds_read_b128 v[132:135], v28 offset:51200
	s_waitcnt lgkmcnt(0)
	v_mfma_f32_16x16x32_f16 v[46:49], v[78:81], v[132:135], v[46:49]
	ds_read_b128 v[144:147], v28 offset:53248
	v_mfma_f32_16x16x32_f16 v[54:57], v[128:131], v[108:111], v[54:57]
	ds_read_b128 v[154:157], v28 offset:55296
	v_mfma_f32_16x16x32_f16 v[70:73], v[128:131], v[132:135], v[70:73]
	s_waitcnt vmcnt(7)
	ds_write_b128 v18, v[112:115]
	s_waitcnt lgkmcnt(2)
	v_mfma_f32_16x16x32_f16 v[104:107], v[78:81], v[144:147], v[104:107]
	s_waitcnt vmcnt(6)
	ds_write_b128 v19, v[116:119]
	s_waitcnt lgkmcnt(2)
	v_mfma_f32_16x16x32_f16 v[22:25], v[78:81], v[154:157], v[22:25]
	ds_read_b128 v[78:81], v16 offset:20480
	v_mfma_f32_16x16x32_f16 v[74:77], v[128:131], v[144:147], v[74:77]
	s_waitcnt vmcnt(5)
	ds_write_b128 v20, v[196:199]
	v_mfma_f32_16x16x32_f16 v[34:37], v[128:131], v[154:157], v[34:37]
	ds_read_b128 v[128:131], v16 offset:22528
	s_waitcnt lgkmcnt(2)
	v_mfma_f32_16x16x32_f16 v[120:123], v[78:81], v[108:111], v[120:123]
	s_waitcnt vmcnt(4)
	ds_write_b128 v17, v[200:203]
	v_mfma_f32_16x16x32_f16 v[124:127], v[78:81], v[132:135], v[124:127]
	s_waitcnt vmcnt(3)
	ds_write_b128 v18, v[140:143] offset:32768
	s_waitcnt lgkmcnt(2)
	v_mfma_f32_16x16x32_f16 v[62:65], v[128:131], v[108:111], v[62:65]
	ds_read_b128 v[108:111], v32 offset:49152
	v_mfma_f32_16x16x32_f16 v[38:41], v[128:131], v[132:135], v[38:41]
	ds_read_b128 v[132:135], v32 offset:51200
	v_mfma_f32_16x16x32_f16 v[136:139], v[78:81], v[144:147], v[136:139]
	s_waitcnt vmcnt(2)
	ds_write_b128 v19, v[204:207] offset:32768
	v_mfma_f32_16x16x32_f16 v[66:69], v[78:81], v[154:157], v[66:69]
	ds_read_b128 v[78:81], v29 offset:16384
	v_mfma_f32_16x16x32_f16 v[50:53], v[128:131], v[144:147], v[50:53]
	ds_read_b128 v[144:147], v32 offset:53248
	v_mfma_f32_16x16x32_f16 v[58:61], v[128:131], v[154:157], v[58:61]
	ds_read_b128 v[128:131], v29 offset:18432
	s_waitcnt lgkmcnt(2)
	v_mfma_f32_16x16x32_f16 v[42:45], v[78:81], v[108:111], v[42:45]
	ds_read_b128 v[154:157], v32 offset:55296
	v_mfma_f32_16x16x32_f16 v[46:49], v[78:81], v[132:135], v[46:49]
	s_waitcnt vmcnt(1)
	ds_write_b128 v20, v[208:211] offset:32768
	s_waitcnt lgkmcnt(2)
	v_mfma_f32_16x16x32_f16 v[54:57], v[128:131], v[108:111], v[54:57]
	s_waitcnt vmcnt(0)
	ds_write_b128 v17, v[212:215] offset:32768
	v_mfma_f32_16x16x32_f16 v[70:73], v[128:131], v[132:135], v[70:73]
	v_mfma_f32_16x16x32_f16 v[104:107], v[78:81], v[144:147], v[104:107]
	s_waitcnt lgkmcnt(2)
	v_mfma_f32_16x16x32_f16 v[22:25], v[78:81], v[154:157], v[22:25]
	ds_read_b128 v[78:81], v29 offset:20480
	v_mfma_f32_16x16x32_f16 v[74:77], v[128:131], v[144:147], v[74:77]
	v_mfma_f32_16x16x32_f16 v[34:37], v[128:131], v[154:157], v[34:37]
	ds_read_b128 v[128:131], v29 offset:22528
	s_waitcnt lgkmcnt(1)
	v_mfma_f32_16x16x32_f16 v[120:123], v[78:81], v[108:111], v[120:123]
	v_mfma_f32_16x16x32_f16 v[124:127], v[78:81], v[132:135], v[124:127]
	s_waitcnt lgkmcnt(0)
	v_mfma_f32_16x16x32_f16 v[62:65], v[128:131], v[108:111], v[62:65]
	v_mfma_f32_16x16x32_f16 v[38:41], v[128:131], v[132:135], v[38:41]
	v_mfma_f32_16x16x32_f16 v[136:139], v[78:81], v[144:147], v[136:139]
	v_mfma_f32_16x16x32_f16 v[66:69], v[78:81], v[154:157], v[66:69]
	global_load_dwordx4 v[78:81], v[0:1], off offset:1152
	global_load_dwordx4 v[108:111], v[2:3], off offset:1152
	global_load_dwordx4 v[158:161], v[4:5], off offset:1152
	global_load_dwordx4 v[162:165], v[8:9], off offset:1152
	global_load_dwordx4 v[132:135], v[6:7], off offset:1152
	global_load_dwordx4 v[166:169], v[10:11], off offset:1152
	global_load_dwordx4 v[188:191], v[12:13], off offset:1152
	global_load_dwordx4 v[192:195], v[14:15], off offset:1152
	s_waitcnt lgkmcnt(0)
	s_barrier
; #define GL_LOAD(s_, kt_) if (VAR != 1) { a##s_##0 = GL_A(0, kt_); a##s_##1 = GL_A(1, kt_); a##s_##2 = GL_A(2, kt_); a##s_##3 = GL_A(3, kt_); b##s_##0 = GL_B(0, kt_); b##s_##1 = GL_B(1, kt_); b##s_##2 = GL_B(2, kt_); b##s_##3 = GL_B(3, kt_); }
; #define LDS_STORE(s_, buf_) if (VAR != 2) { LDS_ST1(sA, 0, buf_, a##s_##0) LDS_ST1(sA, 1, buf_, a##s_##1) LDS_ST1(sA, 2, buf_, a##s_##2) LDS_ST1(sA, 3, buf_, a##s_##3) LDS_ST1(sB, 0, buf_, b##s_##0) LDS_ST1(sB, 1, buf_, b##s_##1) LDS_ST1(sB, 2, buf_, b##s_##2) LDS_ST1(sB, 3, buf_, b##s_##3) }
;     ...
;   GL_LOAD(0, 0)
;   GL_LOAD(1, 1)
;   LDS_STORE(0, 0)
;   if (VAR != 4) __syncthreads();
; #pragma unroll
;   for (int kt = 0; kt < nk; kt += 2) {
;     if (kt + 2 < nk) { GL_LOAD(0, kt + 2) }
;     MMA_TILE(0)
;     LDS_STORE(1, 1)
;     if (VAR != 4) __syncthreads();
;     if (kt + 3 < nk) { GL_LOAD(1, kt + 3) }
;     MMA_TILE(1)
;     if (kt + 2 < nk) { LDS_STORE(0, 0) }
;     if (VAR != 4) __syncthreads();
	v_mfma_f32_16x16x32_f16 v[50:53], v[128:131], v[144:147], v[50:53]
	ds_read_b128 v[112:115], v16
	v_mfma_f32_16x16x32_f16 v[58:61], v[128:131], v[154:157], v[58:61]
	ds_read_b128 v[116:119], v28 offset:32768
	s_waitcnt lgkmcnt(0)
	v_mfma_f32_16x16x32_f16 v[42:45], v[112:115], v[116:119], v[42:45]
	ds_read_b128 v[128:131], v16 offset:2048
	ds_read_b128 v[140:143], v28 offset:34816
	s_waitcnt lgkmcnt(0)
	v_mfma_f32_16x16x32_f16 v[46:49], v[112:115], v[140:143], v[46:49]
	ds_read_b128 v[144:147], v28 offset:36864
	v_mfma_f32_16x16x32_f16 v[54:57], v[128:131], v[116:119], v[54:57]
	ds_read_b128 v[154:157], v28 offset:38912
	v_mfma_f32_16x16x32_f16 v[70:73], v[128:131], v[140:143], v[70:73]
	s_waitcnt vmcnt(7)
	ds_write_b128 v18, v[78:81] offset:16384
	s_waitcnt lgkmcnt(2)
	v_mfma_f32_16x16x32_f16 v[104:107], v[112:115], v[144:147], v[104:107]
	s_waitcnt vmcnt(6)
	ds_write_b128 v19, v[108:111] offset:16384
	s_waitcnt lgkmcnt(2)
	v_mfma_f32_16x16x32_f16 v[22:25], v[112:115], v[154:157], v[22:25]
	ds_read_b128 v[112:115], v16 offset:4096
	v_mfma_f32_16x16x32_f16 v[74:77], v[128:131], v[144:147], v[74:77]
	s_waitcnt vmcnt(5)
	ds_write_b128 v20, v[158:161] offset:16384
	v_mfma_f32_16x16x32_f16 v[34:37], v[128:131], v[154:157], v[34:37]
	ds_read_b128 v[128:131], v16 offset:6144
	s_waitcnt lgkmcnt(2)
	v_mfma_f32_16x16x32_f16 v[120:123], v[112:115], v[116:119], v[120:123]
	s_waitcnt vmcnt(4)
	ds_write_b128 v17, v[162:165] offset:16384
	v_mfma_f32_16x16x32_f16 v[124:127], v[112:115], v[140:143], v[124:127]
	s_waitcnt vmcnt(3)
	ds_write_b128 v18, v[132:135] offset:49152
	s_waitcnt lgkmcnt(2)
	v_mfma_f32_16x16x32_f16 v[62:65], v[128:131], v[116:119], v[62:65]
	ds_read_b128 v[116:119], v32 offset:32768
	v_mfma_f32_16x16x32_f16 v[38:41], v[128:131], v[140:143], v[38:41]
	ds_read_b128 v[140:143], v32 offset:34816
	v_mfma_f32_16x16x32_f16 v[136:139], v[112:115], v[144:147], v[136:139]
	s_waitcnt vmcnt(2)
	ds_write_b128 v19, v[166:169] offset:49152
	v_mfma_f32_16x16x32_f16 v[66:69], v[112:115], v[154:157], v[66:69]
	ds_read_b128 v[112:115], v29
	v_mfma_f32_16x16x32_f16 v[50:53], v[128:131], v[144:147], v[50:53]
	ds_read_b128 v[144:147], v32 offset:36864
	v_mfma_f32_16x16x32_f16 v[58:61], v[128:131], v[154:157], v[58:61]
	ds_read_b128 v[128:131], v29 offset:2048
	s_waitcnt lgkmcnt(2)
	v_mfma_f32_16x16x32_f16 v[42:45], v[112:115], v[116:119], v[42:45]
	ds_read_b128 v[154:157], v32 offset:38912
	v_mfma_f32_16x16x32_f16 v[46:49], v[112:115], v[140:143], v[46:49]
	s_waitcnt vmcnt(1)
	ds_write_b128 v20, v[188:191] offset:49152
	s_waitcnt lgkmcnt(2)
	v_mfma_f32_16x16x32_f16 v[54:57], v[128:131], v[116:119], v[54:57]
	s_waitcnt vmcnt(0)
	ds_write_b128 v17, v[192:195] offset:49152
	v_mfma_f32_16x16x32_f16 v[70:73], v[128:131], v[140:143], v[70:73]
	v_mfma_f32_16x16x32_f16 v[104:107], v[112:115], v[144:147], v[104:107]
	s_waitcnt lgkmcnt(2)
	v_mfma_f32_16x16x32_f16 v[22:25], v[112:115], v[154:157], v[22:25]
	ds_read_b128 v[112:115], v29 offset:4096
	v_mfma_f32_16x16x32_f16 v[74:77], v[128:131], v[144:147], v[74:77]
	v_mfma_f32_16x16x32_f16 v[34:37], v[128:131], v[154:157], v[34:37]
	ds_read_b128 v[128:131], v29 offset:6144
	s_waitcnt lgkmcnt(1)
	v_mfma_f32_16x16x32_f16 v[120:123], v[112:115], v[116:119], v[120:123]
	v_mfma_f32_16x16x32_f16 v[124:127], v[112:115], v[140:143], v[124:127]
	s_waitcnt lgkmcnt(0)
	v_mfma_f32_16x16x32_f16 v[62:65], v[128:131], v[116:119], v[62:65]
	v_mfma_f32_16x16x32_f16 v[38:41], v[128:131], v[140:143], v[38:41]
	v_mfma_f32_16x16x32_f16 v[136:139], v[112:115], v[144:147], v[136:139]
	v_mfma_f32_16x16x32_f16 v[66:69], v[112:115], v[154:157], v[66:69]
	global_load_dwordx4 v[112:115], v[0:1], off offset:1280
	global_load_dwordx4 v[116:119], v[2:3], off offset:1280
	global_load_dwordx4 v[196:199], v[4:5], off offset:1280
	global_load_dwordx4 v[200:203], v[8:9], off offset:1280
	global_load_dwordx4 v[140:143], v[6:7], off offset:1280
	global_load_dwordx4 v[204:207], v[10:11], off offset:1280
	global_load_dwordx4 v[208:211], v[12:13], off offset:1280
	global_load_dwordx4 v[212:215], v[14:15], off offset:1280
	s_waitcnt lgkmcnt(0)
	s_barrier
	v_mfma_f32_16x16x32_f16 v[50:53], v[128:131], v[144:147], v[50:53]
	ds_read_b128 v[78:81], v16 offset:16384
	v_mfma_f32_16x16x32_f16 v[58:61], v[128:131], v[154:157], v[58:61]
	ds_read_b128 v[108:111], v28 offset:49152
	s_waitcnt lgkmcnt(0)
	v_mfma_f32_16x16x32_f16 v[42:45], v[78:81], v[108:111], v[42:45]
	ds_read_b128 v[128:131], v16 offset:18432
	ds_read_b128 v[132:135], v28 offset:51200
	s_waitcnt lgkmcnt(0)
	v_mfma_f32_16x16x32_f16 v[46:49], v[78:81], v[132:135], v[46:49]
	ds_read_b128 v[144:147], v28 offset:53248
	v_mfma_f32_16x16x32_f16 v[54:57], v[128:131], v[108:111], v[54:57]
	ds_read_b128 v[154:157], v28 offset:55296
	v_mfma_f32_16x16x32_f16 v[70:73], v[128:131], v[132:135], v[70:73]
	s_waitcnt vmcnt(7)
	ds_write_b128 v18, v[112:115]
	s_waitcnt lgkmcnt(2)
	v_mfma_f32_16x16x32_f16 v[104:107], v[78:81], v[144:147], v[104:107]
	s_waitcnt vmcnt(6)
	ds_write_b128 v19, v[116:119]
	s_waitcnt lgkmcnt(2)
	v_mfma_f32_16x16x32_f16 v[22:25], v[78:81], v[154:157], v[22:25]
	ds_read_b128 v[78:81], v16 offset:20480
	v_mfma_f32_16x16x32_f16 v[74:77], v[128:131], v[144:147], v[74:77]
	s_waitcnt vmcnt(5)
	ds_write_b128 v20, v[196:199]
	v_mfma_f32_16x16x32_f16 v[34:37], v[128:131], v[154:157], v[34:37]
	ds_read_b128 v[128:131], v16 offset:22528
	s_waitcnt lgkmcnt(2)
	v_mfma_f32_16x16x32_f16 v[120:123], v[78:81], v[108:111], v[120:123]
	s_waitcnt vmcnt(4)
	ds_write_b128 v17, v[200:203]
	v_mfma_f32_16x16x32_f16 v[124:127], v[78:81], v[132:135], v[124:127]
	s_waitcnt vmcnt(3)
	ds_write_b128 v18, v[140:143] offset:32768
	s_waitcnt lgkmcnt(2)
; #define GL_LOAD(s_, kt_) if (VAR != 1) { a##s_##0 = GL_A(0, kt_); a##s_##1 = GL_A(1, kt_); a##s_##2 = GL_A(2, kt_); a##s_##3 = GL_A(3, kt_); b##s_##0 = GL_B(0, kt_); b##s_##1 = GL_B(1, kt_); b##s_##2 = GL_B(2, kt_); b##s_##3 = GL_B(3, kt_); }
; #define LDS_STORE(s_, buf_) if (VAR != 2) { LDS_ST1(sA, 0, buf_, a##s_##0) LDS_ST1(sA, 1, buf_, a##s_##1) LDS_ST1(sA, 2, buf_, a##s_##2) LDS_ST1(sA, 3, buf_, a##s_##3) LDS_ST1(sB, 0, buf_, b##s_##0) LDS_ST1(sB, 1, buf_, b##s_##1) LDS_ST1(sB, 2, buf_, b##s_##2) LDS_ST1(sB, 3, buf_, b##s_##3) }
;     ...
;   GL_LOAD(0, 0)
;   GL_LOAD(1, 1)
;   LDS_STORE(0, 0)
;   if (VAR != 4) __syncthreads();
; #pragma unroll
;   for (int kt = 0; kt < nk; kt += 2) {
;     if (kt + 2 < nk) { GL_LOAD(0, kt + 2) }
;     MMA_TILE(0)
;     LDS_STORE(1, 1)
;     if (VAR != 4) __syncthreads();
;     if (kt + 3 < nk) { GL_LOAD(1, kt + 3) }
;     MMA_TILE(1)
;     if (kt + 2 < nk) { LDS_STORE(0, 0) }
;     if (VAR != 4) __syncthreads();
	v_mfma_f32_16x16x32_f16 v[62:65], v[128:131], v[108:111], v[62:65]
	ds_read_b128 v[108:111], v32 offset:49152
	v_mfma_f32_16x16x32_f16 v[38:41], v[128:131], v[132:135], v[38:41]
	ds_read_b128 v[132:135], v32 offset:51200
	v_mfma_f32_16x16x32_f16 v[136:139], v[78:81], v[144:147], v[136:139]
	s_waitcnt vmcnt(2)
	ds_write_b128 v19, v[204:207] offset:32768
	v_mfma_f32_16x16x32_f16 v[66:69], v[78:81], v[154:157], v[66:69]
	ds_read_b128 v[78:81], v29 offset:16384
	v_mfma_f32_16x16x32_f16 v[50:53], v[128:131], v[144:147], v[50:53]
	ds_read_b128 v[144:147], v32 offset:53248
	v_mfma_f32_16x16x32_f16 v[58:61], v[128:131], v[154:157], v[58:61]
	ds_read_b128 v[128:131], v29 offset:18432
	s_waitcnt lgkmcnt(2)
	v_mfma_f32_16x16x32_f16 v[42:45], v[78:81], v[108:111], v[42:45]
	ds_read_b128 v[154:157], v32 offset:55296
	v_mfma_f32_16x16x32_f16 v[46:49], v[78:81], v[132:135], v[46:49]
	s_waitcnt vmcnt(1)
	ds_write_b128 v20, v[208:211] offset:32768
	s_waitcnt lgkmcnt(2)
	v_mfma_f32_16x16x32_f16 v[54:57], v[128:131], v[108:111], v[54:57]
	s_waitcnt vmcnt(0)
	ds_write_b128 v17, v[212:215] offset:32768
	v_mfma_f32_16x16x32_f16 v[70:73], v[128:131], v[132:135], v[70:73]
	v_mfma_f32_16x16x32_f16 v[104:107], v[78:81], v[144:147], v[104:107]
	s_waitcnt lgkmcnt(2)
	v_mfma_f32_16x16x32_f16 v[22:25], v[78:81], v[154:157], v[22:25]
	ds_read_b128 v[78:81], v29 offset:20480
	v_mfma_f32_16x16x32_f16 v[74:77], v[128:131], v[144:147], v[74:77]
	v_mfma_f32_16x16x32_f16 v[34:37], v[128:131], v[154:157], v[34:37]
	ds_read_b128 v[128:131], v29 offset:22528
	s_waitcnt lgkmcnt(1)
	v_mfma_f32_16x16x32_f16 v[120:123], v[78:81], v[108:111], v[120:123]
	v_mfma_f32_16x16x32_f16 v[124:127], v[78:81], v[132:135], v[124:127]
	s_waitcnt lgkmcnt(0)
	v_mfma_f32_16x16x32_f16 v[62:65], v[128:131], v[108:111], v[62:65]
	v_mfma_f32_16x16x32_f16 v[38:41], v[128:131], v[132:135], v[38:41]
	v_mfma_f32_16x16x32_f16 v[136:139], v[78:81], v[144:147], v[136:139]
	v_mfma_f32_16x16x32_f16 v[66:69], v[78:81], v[154:157], v[66:69]
	global_load_dwordx4 v[78:81], v[0:1], off offset:1408
	global_load_dwordx4 v[108:111], v[2:3], off offset:1408
	global_load_dwordx4 v[158:161], v[4:5], off offset:1408
	global_load_dwordx4 v[162:165], v[8:9], off offset:1408
	global_load_dwordx4 v[132:135], v[6:7], off offset:1408
	global_load_dwordx4 v[166:169], v[10:11], off offset:1408
	global_load_dwordx4 v[188:191], v[12:13], off offset:1408
	global_load_dwordx4 v[192:195], v[14:15], off offset:1408
	s_waitcnt lgkmcnt(0)
	s_barrier
	v_mfma_f32_16x16x32_f16 v[50:53], v[128:131], v[144:147], v[50:53]
	ds_read_b128 v[112:115], v16
	v_mfma_f32_16x16x32_f16 v[58:61], v[128:131], v[154:157], v[58:61]
	ds_read_b128 v[116:119], v28 offset:32768
	s_waitcnt lgkmcnt(0)
	v_mfma_f32_16x16x32_f16 v[42:45], v[112:115], v[116:119], v[42:45]
	ds_read_b128 v[128:131], v16 offset:2048
	ds_read_b128 v[140:143], v28 offset:34816
	s_waitcnt lgkmcnt(0)
	v_mfma_f32_16x16x32_f16 v[46:49], v[112:115], v[140:143], v[46:49]
	ds_read_b128 v[144:147], v28 offset:36864
	v_mfma_f32_16x16x32_f16 v[54:57], v[128:131], v[116:119], v[54:57]
	ds_read_b128 v[154:157], v28 offset:38912
	v_mfma_f32_16x16x32_f16 v[70:73], v[128:131], v[140:143], v[70:73]
	s_waitcnt vmcnt(7)
	ds_write_b128 v18, v[78:81] offset:16384
	s_waitcnt lgkmcnt(2)
	v_mfma_f32_16x16x32_f16 v[104:107], v[112:115], v[144:147], v[104:107]
	s_waitcnt vmcnt(6)
	ds_write_b128 v19, v[108:111] offset:16384
	s_waitcnt lgkmcnt(2)
	v_mfma_f32_16x16x32_f16 v[22:25], v[112:115], v[154:157], v[22:25]
	ds_read_b128 v[112:115], v16 offset:4096
	v_mfma_f32_16x16x32_f16 v[74:77], v[128:131], v[144:147], v[74:77]
	s_waitcnt vmcnt(5)
	ds_write_b128 v20, v[158:161] offset:16384
	v_mfma_f32_16x16x32_f16 v[34:37], v[128:131], v[154:157], v[34:37]
	ds_read_b128 v[128:131], v16 offset:6144
	s_waitcnt lgkmcnt(2)
	v_mfma_f32_16x16x32_f16 v[120:123], v[112:115], v[116:119], v[120:123]
	s_waitcnt vmcnt(4)
	ds_write_b128 v17, v[162:165] offset:16384
	v_mfma_f32_16x16x32_f16 v[124:127], v[112:115], v[140:143], v[124:127]
	s_waitcnt vmcnt(3)
	ds_write_b128 v18, v[132:135] offset:49152
	s_waitcnt lgkmcnt(2)
	v_mfma_f32_16x16x32_f16 v[62:65], v[128:131], v[116:119], v[62:65]
	ds_read_b128 v[116:119], v32 offset:32768
	v_mfma_f32_16x16x32_f16 v[38:41], v[128:131], v[140:143], v[38:41]
	ds_read_b128 v[140:143], v32 offset:34816
	v_mfma_f32_16x16x32_f16 v[136:139], v[112:115], v[144:147], v[136:139]
	s_waitcnt vmcnt(2)
	ds_write_b128 v19, v[166:169] offset:49152
	v_mfma_f32_16x16x32_f16 v[66:69], v[112:115], v[154:157], v[66:69]
	ds_read_b128 v[112:115], v29
	v_mfma_f32_16x16x32_f16 v[50:53], v[128:131], v[144:147], v[50:53]
	ds_read_b128 v[144:147], v32 offset:36864
	v_mfma_f32_16x16x32_f16 v[58:61], v[128:131], v[154:157], v[58:61]
	ds_read_b128 v[128:131], v29 offset:2048
	s_waitcnt lgkmcnt(2)
	v_mfma_f32_16x16x32_f16 v[42:45], v[112:115], v[116:119], v[42:45]
	ds_read_b128 v[154:157], v32 offset:38912
	v_mfma_f32_16x16x32_f16 v[46:49], v[112:115], v[140:143], v[46:49]
	s_waitcnt vmcnt(1)
	ds_write_b128 v20, v[188:191] offset:49152
	s_waitcnt lgkmcnt(2)
	v_mfma_f32_16x16x32_f16 v[54:57], v[128:131], v[116:119], v[54:57]
	s_waitcnt vmcnt(0)
	ds_write_b128 v17, v[192:195] offset:49152
	v_mfma_f32_16x16x32_f16 v[70:73], v[128:131], v[140:143], v[70:73]
	v_mfma_f32_16x16x32_f16 v[104:107], v[112:115], v[144:147], v[104:107]
	s_waitcnt lgkmcnt(2)
	v_mfma_f32_16x16x32_f16 v[22:25], v[112:115], v[154:157], v[22:25]
	ds_read_b128 v[112:115], v29 offset:4096
	v_mfma_f32_16x16x32_f16 v[74:77], v[128:131], v[144:147], v[74:77]
	v_mfma_f32_16x16x32_f16 v[34:37], v[128:131], v[154:157], v[34:37]
	ds_read_b128 v[128:131], v29 offset:6144
	s_waitcnt lgkmcnt(1)
	v_mfma_f32_16x16x32_f16 v[120:123], v[112:115], v[116:119], v[120:123]
	v_mfma_f32_16x16x32_f16 v[124:127], v[112:115], v[140:143], v[124:127]
	s_waitcnt lgkmcnt(0)
	v_mfma_f32_16x16x32_f16 v[62:65], v[128:131], v[116:119], v[62:65]
	v_mfma_f32_16x16x32_f16 v[38:41], v[128:131], v[140:143], v[38:41]
	v_mfma_f32_16x16x32_f16 v[136:139], v[112:115], v[144:147], v[136:139]
	v_mfma_f32_16x16x32_f16 v[66:69], v[112:115], v[154:157], v[66:69]
	global_load_dwordx4 v[112:115], v[0:1], off offset:1536
	global_load_dwordx4 v[116:119], v[2:3], off offset:1536
	global_load_dwordx4 v[196:199], v[4:5], off offset:1536
	global_load_dwordx4 v[200:203], v[8:9], off offset:1536
	global_load_dwordx4 v[140:143], v[6:7], off offset:1536
	global_load_dwordx4 v[204:207], v[10:11], off offset:1536
	global_load_dwordx4 v[208:211], v[12:13], off offset:1536
	global_load_dwordx4 v[212:215], v[14:15], off offset:1536
	s_waitcnt lgkmcnt(0)
	s_barrier
; #define GL_LOAD(s_, kt_) if (VAR != 1) { a##s_##0 = GL_A(0, kt_); a##s_##1 = GL_A(1, kt_); a##s_##2 = GL_A(2, kt_); a##s_##3 = GL_A(3, kt_); b##s_##0 = GL_B(0, kt_); b##s_##1 = GL_B(1, kt_); b##s_##2 = GL_B(2, kt_); b##s_##3 = GL_B(3, kt_); }
; #define LDS_STORE(s_, buf_) if (VAR != 2) { LDS_ST1(sA, 0, buf_, a##s_##0) LDS_ST1(sA, 1, buf_, a##s_##1) LDS_ST1(sA, 2, buf_, a##s_##2) LDS_ST1(sA, 3, buf_, a##s_##3) LDS_ST1(sB, 0, buf_, b##s_##0) LDS_ST1(sB, 1, buf_, b##s_##1) LDS_ST1(sB, 2, buf_, b##s_##2) LDS_ST1(sB, 3, buf_, b##s_##3) }
;     ...
;   GL_LOAD(0, 0)
;   GL_LOAD(1, 1)
;   LDS_STORE(0, 0)
;   if (VAR != 4) __syncthreads();
; #pragma unroll
;   for (int kt = 0; kt < nk; kt += 2) {
;     if (kt + 2 < nk) { GL_LOAD(0, kt + 2) }
;     MMA_TILE(0)
;     LDS_STORE(1, 1)
;     if (VAR != 4) __syncthreads();
;     if (kt + 3 < nk) { GL_LOAD(1, kt + 3) }
;     MMA_TILE(1)
;     if (kt + 2 < nk) { LDS_STORE(0, 0) }
;     if (VAR != 4) __syncthreads();
	v_mfma_f32_16x16x32_f16 v[50:53], v[128:131], v[144:147], v[50:53]
	ds_read_b128 v[78:81], v16 offset:16384
	v_mfma_f32_16x16x32_f16 v[58:61], v[128:131], v[154:157], v[58:61]
	ds_read_b128 v[108:111], v28 offset:49152
	s_waitcnt lgkmcnt(0)
	v_mfma_f32_16x16x32_f16 v[42:45], v[78:81], v[108:111], v[42:45]
	ds_read_b128 v[128:131], v16 offset:18432
	ds_read_b128 v[132:135], v28 offset:51200
	s_waitcnt lgkmcnt(0)
	v_mfma_f32_16x16x32_f16 v[46:49], v[78:81], v[132:135], v[46:49]
	ds_read_b128 v[144:147], v28 offset:53248
	v_mfma_f32_16x16x32_f16 v[54:57], v[128:131], v[108:111], v[54:57]
	ds_read_b128 v[154:157], v28 offset:55296
	v_mfma_f32_16x16x32_f16 v[70:73], v[128:131], v[132:135], v[70:73]
	s_waitcnt vmcnt(7)
	ds_write_b128 v18, v[112:115]
	s_waitcnt lgkmcnt(2)
	v_mfma_f32_16x16x32_f16 v[104:107], v[78:81], v[144:147], v[104:107]
	s_waitcnt vmcnt(6)
	ds_write_b128 v19, v[116:119]
	s_waitcnt lgkmcnt(2)
	v_mfma_f32_16x16x32_f16 v[22:25], v[78:81], v[154:157], v[22:25]
	ds_read_b128 v[78:81], v16 offset:20480
	v_mfma_f32_16x16x32_f16 v[74:77], v[128:131], v[144:147], v[74:77]
	s_waitcnt vmcnt(5)
	ds_write_b128 v20, v[196:199]
	v_mfma_f32_16x16x32_f16 v[34:37], v[128:131], v[154:157], v[34:37]
	ds_read_b128 v[128:131], v16 offset:22528
	s_waitcnt lgkmcnt(2)
	v_mfma_f32_16x16x32_f16 v[120:123], v[78:81], v[108:111], v[120:123]
	s_waitcnt vmcnt(4)
	ds_write_b128 v17, v[200:203]
	v_mfma_f32_16x16x32_f16 v[124:127], v[78:81], v[132:135], v[124:127]
	s_waitcnt vmcnt(3)
	ds_write_b128 v18, v[140:143] offset:32768
	s_waitcnt lgkmcnt(2)
	v_mfma_f32_16x16x32_f16 v[62:65], v[128:131], v[108:111], v[62:65]
	ds_read_b128 v[108:111], v32 offset:49152
	v_mfma_f32_16x16x32_f16 v[38:41], v[128:131], v[132:135], v[38:41]
	ds_read_b128 v[132:135], v32 offset:51200
	v_mfma_f32_16x16x32_f16 v[136:139], v[78:81], v[144:147], v[136:139]
	s_waitcnt vmcnt(2)
	ds_write_b128 v19, v[204:207] offset:32768
	v_mfma_f32_16x16x32_f16 v[66:69], v[78:81], v[154:157], v[66:69]
	ds_read_b128 v[78:81], v29 offset:16384
	v_mfma_f32_16x16x32_f16 v[50:53], v[128:131], v[144:147], v[50:53]
	ds_read_b128 v[144:147], v32 offset:53248
	v_mfma_f32_16x16x32_f16 v[58:61], v[128:131], v[154:157], v[58:61]
	ds_read_b128 v[128:131], v29 offset:18432
	s_waitcnt lgkmcnt(2)
	v_mfma_f32_16x16x32_f16 v[42:45], v[78:81], v[108:111], v[42:45]
	ds_read_b128 v[154:157], v32 offset:55296
	v_mfma_f32_16x16x32_f16 v[46:49], v[78:81], v[132:135], v[46:49]
	s_waitcnt vmcnt(1)
	ds_write_b128 v20, v[208:211] offset:32768
	s_waitcnt lgkmcnt(2)
	v_mfma_f32_16x16x32_f16 v[54:57], v[128:131], v[108:111], v[54:57]
	s_waitcnt vmcnt(0)
	ds_write_b128 v17, v[212:215] offset:32768
	v_mfma_f32_16x16x32_f16 v[70:73], v[128:131], v[132:135], v[70:73]
	v_mfma_f32_16x16x32_f16 v[104:107], v[78:81], v[144:147], v[104:107]
	s_waitcnt lgkmcnt(2)
	v_mfma_f32_16x16x32_f16 v[22:25], v[78:81], v[154:157], v[22:25]
	ds_read_b128 v[78:81], v29 offset:20480
	v_mfma_f32_16x16x32_f16 v[74:77], v[128:131], v[144:147], v[74:77]
	v_mfma_f32_16x16x32_f16 v[34:37], v[128:131], v[154:157], v[34:37]
	ds_read_b128 v[128:131], v29 offset:22528
	s_waitcnt lgkmcnt(1)
	v_mfma_f32_16x16x32_f16 v[120:123], v[78:81], v[108:111], v[120:123]
	v_mfma_f32_16x16x32_f16 v[124:127], v[78:81], v[132:135], v[124:127]
	s_waitcnt lgkmcnt(0)
	v_mfma_f32_16x16x32_f16 v[62:65], v[128:131], v[108:111], v[62:65]
	v_mfma_f32_16x16x32_f16 v[38:41], v[128:131], v[132:135], v[38:41]
	v_mfma_f32_16x16x32_f16 v[136:139], v[78:81], v[144:147], v[136:139]
	v_mfma_f32_16x16x32_f16 v[66:69], v[78:81], v[154:157], v[66:69]
	global_load_dwordx4 v[78:81], v[0:1], off offset:1664
	global_load_dwordx4 v[108:111], v[2:3], off offset:1664
	global_load_dwordx4 v[158:161], v[4:5], off offset:1664
	global_load_dwordx4 v[162:165], v[8:9], off offset:1664
	global_load_dwordx4 v[132:135], v[6:7], off offset:1664
	global_load_dwordx4 v[166:169], v[10:11], off offset:1664
	global_load_dwordx4 v[188:191], v[12:13], off offset:1664
	global_load_dwordx4 v[192:195], v[14:15], off offset:1664
	s_waitcnt lgkmcnt(0)
	s_barrier
	v_mfma_f32_16x16x32_f16 v[50:53], v[128:131], v[144:147], v[50:53]
	ds_read_b128 v[112:115], v16
	v_mfma_f32_16x16x32_f16 v[58:61], v[128:131], v[154:157], v[58:61]
	ds_read_b128 v[116:119], v28 offset:32768
	s_waitcnt lgkmcnt(0)
	v_mfma_f32_16x16x32_f16 v[42:45], v[112:115], v[116:119], v[42:45]
	ds_read_b128 v[128:131], v16 offset:2048
	ds_read_b128 v[140:143], v28 offset:34816
	s_waitcnt lgkmcnt(0)
	v_mfma_f32_16x16x32_f16 v[46:49], v[112:115], v[140:143], v[46:49]
	ds_read_b128 v[144:147], v28 offset:36864
	v_mfma_f32_16x16x32_f16 v[54:57], v[128:131], v[116:119], v[54:57]
	ds_read_b128 v[154:157], v28 offset:38912
	v_mfma_f32_16x16x32_f16 v[70:73], v[128:131], v[140:143], v[70:73]
	s_waitcnt vmcnt(7)
	ds_write_b128 v18, v[78:81] offset:16384
	s_waitcnt lgkmcnt(2)
	v_mfma_f32_16x16x32_f16 v[104:107], v[112:115], v[144:147], v[104:107]
	s_waitcnt vmcnt(6)
	ds_write_b128 v19, v[108:111] offset:16384
	s_waitcnt lgkmcnt(2)
	v_mfma_f32_16x16x32_f16 v[22:25], v[112:115], v[154:157], v[22:25]
	ds_read_b128 v[112:115], v16 offset:4096
	v_mfma_f32_16x16x32_f16 v[74:77], v[128:131], v[144:147], v[74:77]
	s_waitcnt vmcnt(5)
	ds_write_b128 v20, v[158:161] offset:16384
	v_mfma_f32_16x16x32_f16 v[34:37], v[128:131], v[154:157], v[34:37]
	ds_read_b128 v[128:131], v16 offset:6144
	s_waitcnt lgkmcnt(2)
	v_mfma_f32_16x16x32_f16 v[120:123], v[112:115], v[116:119], v[120:123]
	s_waitcnt vmcnt(4)
	ds_write_b128 v17, v[162:165] offset:16384
	v_mfma_f32_16x16x32_f16 v[124:127], v[112:115], v[140:143], v[124:127]
	s_waitcnt vmcnt(3)
	ds_write_b128 v18, v[132:135] offset:49152
	s_waitcnt lgkmcnt(2)
; #define GL_LOAD(s_, kt_) if (VAR != 1) { a##s_##0 = GL_A(0, kt_); a##s_##1 = GL_A(1, kt_); a##s_##2 = GL_A(2, kt_); a##s_##3 = GL_A(3, kt_); b##s_##0 = GL_B(0, kt_); b##s_##1 = GL_B(1, kt_); b##s_##2 = GL_B(2, kt_); b##s_##3 = GL_B(3, kt_); }
; #define LDS_STORE(s_, buf_) if (VAR != 2) { LDS_ST1(sA, 0, buf_, a##s_##0) LDS_ST1(sA, 1, buf_, a##s_##1) LDS_ST1(sA, 2, buf_, a##s_##2) LDS_ST1(sA, 3, buf_, a##s_##3) LDS_ST1(sB, 0, buf_, b##s_##0) LDS_ST1(sB, 1, buf_, b##s_##1) LDS_ST1(sB, 2, buf_, b##s_##2) LDS_ST1(sB, 3, buf_, b##s_##3) }
;     ...
;   GL_LOAD(0, 0)
;   GL_LOAD(1, 1)
;   LDS_STORE(0, 0)
;   if (VAR != 4) __syncthreads();
; #pragma unroll
;   for (int kt = 0; kt < nk; kt += 2) {
;     if (kt + 2 < nk) { GL_LOAD(0, kt + 2) }
;     MMA_TILE(0)
;     LDS_STORE(1, 1)
;     if (VAR != 4) __syncthreads();
;     if (kt + 3 < nk) { GL_LOAD(1, kt + 3) }
;     MMA_TILE(1)
;     if (kt + 2 < nk) { LDS_STORE(0, 0) }
;     if (VAR != 4) __syncthreads();
	v_mfma_f32_16x16x32_f16 v[62:65], v[128:131], v[116:119], v[62:65]
	ds_read_b128 v[116:119], v32 offset:32768
	v_mfma_f32_16x16x32_f16 v[38:41], v[128:131], v[140:143], v[38:41]
	ds_read_b128 v[140:143], v32 offset:34816
	v_mfma_f32_16x16x32_f16 v[136:139], v[112:115], v[144:147], v[136:139]
	s_waitcnt vmcnt(2)
	ds_write_b128 v19, v[166:169] offset:49152
	v_mfma_f32_16x16x32_f16 v[66:69], v[112:115], v[154:157], v[66:69]
	ds_read_b128 v[112:115], v29
	v_mfma_f32_16x16x32_f16 v[50:53], v[128:131], v[144:147], v[50:53]
	ds_read_b128 v[144:147], v32 offset:36864
	v_mfma_f32_16x16x32_f16 v[58:61], v[128:131], v[154:157], v[58:61]
	ds_read_b128 v[128:131], v29 offset:2048
	s_waitcnt lgkmcnt(2)
	v_mfma_f32_16x16x32_f16 v[42:45], v[112:115], v[116:119], v[42:45]
	ds_read_b128 v[154:157], v32 offset:38912
	v_mfma_f32_16x16x32_f16 v[46:49], v[112:115], v[140:143], v[46:49]
	s_waitcnt vmcnt(1)
	ds_write_b128 v20, v[188:191] offset:49152
	s_waitcnt lgkmcnt(2)
	v_mfma_f32_16x16x32_f16 v[54:57], v[128:131], v[116:119], v[54:57]
	s_waitcnt vmcnt(0)
	ds_write_b128 v17, v[192:195] offset:49152
	v_mfma_f32_16x16x32_f16 v[70:73], v[128:131], v[140:143], v[70:73]
	v_mfma_f32_16x16x32_f16 v[104:107], v[112:115], v[144:147], v[104:107]
	s_waitcnt lgkmcnt(2)
	v_mfma_f32_16x16x32_f16 v[22:25], v[112:115], v[154:157], v[22:25]
	ds_read_b128 v[112:115], v29 offset:4096
	v_mfma_f32_16x16x32_f16 v[74:77], v[128:131], v[144:147], v[74:77]
	v_mfma_f32_16x16x32_f16 v[34:37], v[128:131], v[154:157], v[34:37]
	ds_read_b128 v[128:131], v29 offset:6144
	s_waitcnt lgkmcnt(1)
	v_mfma_f32_16x16x32_f16 v[120:123], v[112:115], v[116:119], v[120:123]
	v_mfma_f32_16x16x32_f16 v[124:127], v[112:115], v[140:143], v[124:127]
	s_waitcnt lgkmcnt(0)
	v_mfma_f32_16x16x32_f16 v[62:65], v[128:131], v[116:119], v[62:65]
	v_mfma_f32_16x16x32_f16 v[38:41], v[128:131], v[140:143], v[38:41]
	v_mfma_f32_16x16x32_f16 v[136:139], v[112:115], v[144:147], v[136:139]
	v_mfma_f32_16x16x32_f16 v[66:69], v[112:115], v[154:157], v[66:69]
	global_load_dwordx4 v[112:115], v[0:1], off offset:1792
	global_load_dwordx4 v[116:119], v[2:3], off offset:1792
	global_load_dwordx4 v[196:199], v[4:5], off offset:1792
	global_load_dwordx4 v[200:203], v[8:9], off offset:1792
	global_load_dwordx4 v[140:143], v[6:7], off offset:1792
	global_load_dwordx4 v[204:207], v[10:11], off offset:1792
	global_load_dwordx4 v[208:211], v[12:13], off offset:1792
	global_load_dwordx4 v[212:215], v[14:15], off offset:1792
	s_waitcnt lgkmcnt(0)
	s_barrier
	v_mfma_f32_16x16x32_f16 v[50:53], v[128:131], v[144:147], v[50:53]
	ds_read_b128 v[78:81], v16 offset:16384
	v_mfma_f32_16x16x32_f16 v[58:61], v[128:131], v[154:157], v[58:61]
	ds_read_b128 v[108:111], v28 offset:49152
	s_waitcnt lgkmcnt(0)
	v_mfma_f32_16x16x32_f16 v[42:45], v[78:81], v[108:111], v[42:45]
	ds_read_b128 v[128:131], v16 offset:18432
	ds_read_b128 v[132:135], v28 offset:51200
	s_waitcnt lgkmcnt(0)
	v_mfma_f32_16x16x32_f16 v[46:49], v[78:81], v[132:135], v[46:49]
	ds_read_b128 v[144:147], v28 offset:53248
	v_mfma_f32_16x16x32_f16 v[54:57], v[128:131], v[108:111], v[54:57]
	ds_read_b128 v[154:157], v28 offset:55296
	v_mfma_f32_16x16x32_f16 v[70:73], v[128:131], v[132:135], v[70:73]
	s_waitcnt vmcnt(7)
	ds_write_b128 v18, v[112:115]
	s_waitcnt lgkmcnt(2)
	v_mfma_f32_16x16x32_f16 v[104:107], v[78:81], v[144:147], v[104:107]
	s_waitcnt vmcnt(6)
	ds_write_b128 v19, v[116:119]
	s_waitcnt lgkmcnt(2)
	v_mfma_f32_16x16x32_f16 v[22:25], v[78:81], v[154:157], v[22:25]
	ds_read_b128 v[78:81], v16 offset:20480
	v_mfma_f32_16x16x32_f16 v[74:77], v[128:131], v[144:147], v[74:77]
	s_waitcnt vmcnt(5)
	ds_write_b128 v20, v[196:199]
	v_mfma_f32_16x16x32_f16 v[34:37], v[128:131], v[154:157], v[34:37]
	ds_read_b128 v[128:131], v16 offset:22528
	s_waitcnt lgkmcnt(2)
	v_mfma_f32_16x16x32_f16 v[120:123], v[78:81], v[108:111], v[120:123]
	s_waitcnt vmcnt(4)
	ds_write_b128 v17, v[200:203]
	v_mfma_f32_16x16x32_f16 v[124:127], v[78:81], v[132:135], v[124:127]
	s_waitcnt vmcnt(3)
	ds_write_b128 v18, v[140:143] offset:32768
	s_waitcnt lgkmcnt(2)
	v_mfma_f32_16x16x32_f16 v[62:65], v[128:131], v[108:111], v[62:65]
	ds_read_b128 v[108:111], v32 offset:49152
	v_mfma_f32_16x16x32_f16 v[38:41], v[128:131], v[132:135], v[38:41]
	ds_read_b128 v[132:135], v32 offset:51200
	v_mfma_f32_16x16x32_f16 v[136:139], v[78:81], v[144:147], v[136:139]
	s_waitcnt vmcnt(2)
	ds_write_b128 v19, v[204:207] offset:32768
	v_mfma_f32_16x16x32_f16 v[66:69], v[78:81], v[154:157], v[66:69]
	ds_read_b128 v[78:81], v29 offset:16384
	v_mfma_f32_16x16x32_f16 v[50:53], v[128:131], v[144:147], v[50:53]
	ds_read_b128 v[144:147], v32 offset:53248
	v_mfma_f32_16x16x32_f16 v[58:61], v[128:131], v[154:157], v[58:61]
	ds_read_b128 v[128:131], v29 offset:18432
	s_waitcnt lgkmcnt(2)
	v_mfma_f32_16x16x32_f16 v[42:45], v[78:81], v[108:111], v[42:45]
	ds_read_b128 v[154:157], v32 offset:55296
	v_mfma_f32_16x16x32_f16 v[46:49], v[78:81], v[132:135], v[46:49]
	s_waitcnt vmcnt(1)
	ds_write_b128 v20, v[208:211] offset:32768
	s_waitcnt lgkmcnt(2)
	v_mfma_f32_16x16x32_f16 v[54:57], v[128:131], v[108:111], v[54:57]
	s_waitcnt vmcnt(0)
	ds_write_b128 v17, v[212:215] offset:32768
	v_mfma_f32_16x16x32_f16 v[70:73], v[128:131], v[132:135], v[70:73]
	v_mfma_f32_16x16x32_f16 v[104:107], v[78:81], v[144:147], v[104:107]
	s_waitcnt lgkmcnt(2)
	v_mfma_f32_16x16x32_f16 v[22:25], v[78:81], v[154:157], v[22:25]
	ds_read_b128 v[78:81], v29 offset:20480
	v_mfma_f32_16x16x32_f16 v[74:77], v[128:131], v[144:147], v[74:77]
	v_mfma_f32_16x16x32_f16 v[34:37], v[128:131], v[154:157], v[34:37]
	ds_read_b128 v[128:131], v29 offset:22528
	s_waitcnt lgkmcnt(1)
	v_mfma_f32_16x16x32_f16 v[120:123], v[78:81], v[108:111], v[120:123]
	v_mfma_f32_16x16x32_f16 v[124:127], v[78:81], v[132:135], v[124:127]
	s_waitcnt lgkmcnt(0)
	v_mfma_f32_16x16x32_f16 v[62:65], v[128:131], v[108:111], v[62:65]
	v_mfma_f32_16x16x32_f16 v[38:41], v[128:131], v[132:135], v[38:41]
	v_mfma_f32_16x16x32_f16 v[136:139], v[78:81], v[144:147], v[136:139]
	v_mfma_f32_16x16x32_f16 v[66:69], v[78:81], v[154:157], v[66:69]
	global_load_dwordx4 v[80:83], v[0:1], off offset:1920
	global_load_dwordx4 v[108:111], v[2:3], off offset:1920
	global_load_dwordx4 v[158:161], v[4:5], off offset:1920
	global_load_dwordx4 v[162:165], v[8:9], off offset:1920
	global_load_dwordx4 v[132:135], v[6:7], off offset:1920
	global_load_dwordx4 v[166:169], v[10:11], off offset:1920
	global_load_dwordx4 v[188:191], v[12:13], off offset:1920
	global_load_dwordx4 v[12:15], v[14:15], off offset:1920
	s_waitcnt lgkmcnt(0)
	s_barrier
; DI unsigned pack2(float lo, float hi) { f2_t v = {lo, hi}; h2_t b = __builtin_convertvector(v, h2_t); return __builtin_bit_cast(unsigned, b); }
; #define GL_LOAD(s_, kt_) if (VAR != 1) { a##s_##0 = GL_A(0, kt_); a##s_##1 = GL_A(1, kt_); a##s_##2 = GL_A(2, kt_); a##s_##3 = GL_A(3, kt_); b##s_##0 = GL_B(0, kt_); b##s_##1 = GL_B(1, kt_); b##s_##2 = GL_B(2, kt_); b##s_##3 = GL_B(3, kt_); }
; #define LDS_STORE(s_, buf_) if (VAR != 2) { LDS_ST1(sA, 0, buf_, a##s_##0) LDS_ST1(sA, 1, buf_, a##s_##1) LDS_ST1(sA, 2, buf_, a##s_##2) LDS_ST1(sA, 3, buf_, a##s_##3) LDS_ST1(sB, 0, buf_, b##s_##0) LDS_ST1(sB, 1, buf_, b##s_##1) LDS_ST1(sB, 2, buf_, b##s_##2) LDS_ST1(sB, 3, buf_, b##s_##3) }
;     ...
;   for (int kt = 0; kt < nk; kt += 2) {
;     if (kt + 2 < nk) { GL_LOAD(0, kt + 2) }
;     MMA_TILE(0)
;     LDS_STORE(1, 1)
;     if (VAR != 4) __syncthreads();
;     if (kt + 3 < nk) { GL_LOAD(1, kt + 3) }
;     MMA_TILE(1)
;     if (kt + 2 < nk) { LDS_STORE(0, 0) }
;     if (VAR != 4) __syncthreads();
; DI void phase_proj(const Params& P, int l, char* smem) {
;     ...
;       const int cb = col0 - PW;
;       const int br = cb >> 9, c0 = cb & 511;
;       const int b = row0 >> 12, s0 = row0 & 4095;
; #pragma unroll
;       for (int mt = 0; mt < 4; ++mt) {
;         float r4[4];
; #pragma unroll
;         for (int j = 0; j < 4; ++j) r4[j] = __shfl(rs[mt], 4 * g + j);
; #pragma unroll
;         for (int nt = 0; nt < 4; ++nt) {
;           const int c = c0 + nt * 16 + lr;
;           bf16_t* dst = VT + ((size_t)(br * NB + b) * 512 + c) * SEQ + s0 + mt * 16 + 4 * g;
;           *(uint2*)dst = make_uint2(pack2(acc[mt][nt][0] * r4[0], acc[mt][nt][1] * r4[1]), pack2(acc[mt][nt][2] * r4[2], acc[mt][nt][3] * r4[3]));
;         }
;       }
	ds_read_b128 v[0:3], v16
	v_mfma_f32_16x16x32_f16 v[50:53], v[128:131], v[144:147], v[50:53]
	v_mfma_f32_16x16x32_f16 v[112:115], v[128:131], v[154:157], v[58:61]
	ds_read_b128 v[116:119], v28 offset:32768
	ds_read_b128 v[4:7], v16 offset:2048
	ds_read_b128 v[128:131], v28 offset:34816
	s_waitcnt lgkmcnt(2)
	v_mfma_f32_16x16x32_f16 v[140:143], v[0:3], v[116:119], v[42:45]
	s_waitcnt lgkmcnt(0)
	v_mfma_f32_16x16x32_f16 v[144:147], v[0:3], v[128:131], v[46:49]
	s_nop 0
	ds_read_b128 v[42:45], v28 offset:36864
	s_nop 0
	ds_read_b128 v[46:49], v28 offset:38912
	s_waitcnt lgkmcnt(0)
	v_mfma_f32_16x16x32_f16 v[154:157], v[0:3], v[46:49], v[22:25]
	v_mfma_f32_16x16x32_f16 v[204:207], v[4:7], v[46:49], v[34:37]
	s_nop 1
	ds_read_b128 v[22:25], v16 offset:4096
	ds_read_b128 v[34:37], v16 offset:6144
	ds_read_b128 v[208:211], v29
	ds_read_b128 v[212:215], v29 offset:2048
	v_mfma_f32_16x16x32_f16 v[104:107], v[0:3], v[42:45], v[104:107]
	v_mfma_f32_16x16x32_f16 v[192:195], v[4:7], v[116:119], v[54:57]
	v_mfma_f32_16x16x32_f16 v[200:203], v[4:7], v[42:45], v[74:77]
	s_nop 2
	ds_read_b128 v[76:79], v32 offset:32768
	ds_read_b128 v[56:59], v32 offset:34816
	ds_read_b128 v[220:223], v29 offset:4096
	ds_read_b128 v[0:3], v29 offset:6144
	v_mfma_f32_16x16x32_f16 v[196:199], v[4:7], v[128:131], v[70:73]
	ds_read_b128 v[8:11], v32 offset:36864
	ds_read_b128 v[4:7], v32 offset:38912
	s_waitcnt vmcnt(7)
	ds_write_b128 v18, v[80:83] offset:16384
	s_waitcnt lgkmcnt(10)
	v_mfma_f32_16x16x32_f16 v[120:123], v[22:25], v[116:119], v[120:123]
	s_waitcnt vmcnt(6)
	ds_write_b128 v19, v[108:111] offset:16384
	s_waitcnt vmcnt(5)
	ds_write_b128 v20, v[158:161] offset:16384
	s_waitcnt vmcnt(4)
	ds_write_b128 v17, v[162:165] offset:16384
	s_waitcnt vmcnt(3)
	ds_write_b128 v18, v[132:135] offset:49152
	s_waitcnt vmcnt(2)
	ds_write_b128 v19, v[166:169] offset:49152
	s_waitcnt vmcnt(1)
	ds_write_b128 v20, v[188:191] offset:49152
	v_mfma_f32_16x16x32_f16 v[136:139], v[22:25], v[42:45], v[136:139]
	s_waitcnt vmcnt(0)
	ds_write_b128 v17, v[12:15] offset:49152
	s_waitcnt lgkmcnt(0)
	s_barrier
	v_mfma_f32_16x16x32_f16 v[224:227], v[22:25], v[46:49], v[66:69]
	v_and_or_b32 v188, v94, s1, v97
	v_ashrrev_i32_e32 v94, 7, v94
	v_mfma_f32_16x16x32_f16 v[108:111], v[34:37], v[116:119], v[62:65]
	ds_read_b128 v[116:119], v16 offset:16384
	ds_read_b128 v[80:83], v16 offset:18432
	v_and_b32_e32 v94, -4, v94
	v_add_u32_e32 v94, v94, v95
	v_mfma_f32_16x16x32_f16 v[72:75], v[34:37], v[128:131], v[38:41]
	v_ashrrev_i32_e32 v95, 31, v94
	v_lshlrev_b64 v[170:171], 21, v[94:95]
	v_lshl_add_u64 v[94:95], v[92:93], 0, v[150:151]
	v_mfma_f32_16x16x32_f16 v[40:43], v[34:37], v[42:45], v[50:53]
	v_lshlrev_b32_e32 v150, 2, v103
	v_lshl_or_b32 v170, v188, 12, v170
	ds_bpermute_b32 v188, v150, v98
	v_mfma_f32_16x16x32_f16 v[44:47], v[34:37], v[46:49], v[112:115]
	ds_bpermute_b32 v189, v150, v98 offset:4
	ds_bpermute_b32 v190, v150, v98 offset:8
	v_mfma_f32_16x16x32_f16 v[112:115], v[208:211], v[76:79], v[140:143]
	v_mfma_f32_16x16x32_f16 v[124:127], v[22:25], v[128:131], v[124:127]
	ds_read_b128 v[36:39], v28 offset:49152
	ds_read_b128 v[24:27], v28 offset:51200
	ds_read_b128 v[64:67], v16 offset:20480
	ds_read_b128 v[12:15], v16 offset:22528
	ds_read_b128 v[20:23], v28 offset:53248
	ds_read_b128 v[16:19], v28 offset:55296
	ds_read_b128 v[128:131], v29 offset:16384
	ds_read_b128 v[132:135], v29 offset:18432
	ds_read_b128 v[60:63], v32 offset:49152
	ds_read_b128 v[52:55], v32 offset:51200
	ds_read_b128 v[68:71], v29 offset:20480
	ds_read_b128 v[28:31], v29 offset:22528
	s_waitcnt lgkmcnt(11)
	v_mfma_f32_16x16x32_f16 v[112:115], v[116:119], v[36:39], v[112:115]
	ds_read_b128 v[48:51], v32 offset:53248
	ds_read_b128 v[32:35], v32 offset:55296
	s_waitcnt lgkmcnt(0)
	s_barrier
	s_setprio 0
	v_mfma_f32_16x16x32_f16 v[140:143], v[208:211], v[56:59], v[144:147]
	v_mfma_f32_16x16x32_f16 v[144:147], v[208:211], v[4:7], v[154:157]
	v_mfma_f32_16x16x32_f16 v[154:157], v[212:215], v[76:79], v[192:195]
	s_nop 2
	v_or_b32_e32 v194, 12, v150
	ds_bpermute_b32 v191, v194, v98
	v_mfma_f32_16x16x32_f16 v[112:115], v[128:131], v[60:63], v[112:115]
	v_lshl_add_u64 v[98:99], v[170:171], 1, v[94:95]
	v_mfma_f32_16x16x32_f16 v[104:107], v[208:211], v[8:11], v[104:107]
	v_mfma_f32_16x16x32_f16 v[104:107], v[116:119], v[20:23], v[104:107]
	s_nop 4
	v_mul_f32_e64 v112, v112, v188
	v_mul_f32_e64 v113, v113, v189
	s_waitcnt lgkmcnt(0)
	v_pk_mul_f32 v[114:115], v[114:115], v[190:191]
	v_cvt_pk_f16_f32 v112, v112, v113
	v_cvt_pk_f16_f32 v113, v114, v115
	v_mov_b32_e32 v228, v112
	v_mov_b32_e32 v229, v113
	v_mfma_f32_16x16x32_f16 v[112:115], v[116:119], v[24:27], v[140:143]
	v_mfma_f32_16x16x32_f16 v[112:115], v[128:131], v[52:55], v[112:115]
	s_nop 1
	v_or_b32_e32 v140, 0x10000, v170
	v_mov_b32_e32 v141, v171
	v_lshlrev_b64 v[140:141], 1, v[140:141]
	v_mfma_f32_16x16x32_f16 v[104:107], v[128:131], v[48:51], v[104:107]
	v_lshl_add_u64 v[142:143], v[94:95], 0, v[140:141]
	s_nop 0
	v_pk_mul_f32 v[112:113], v[112:113], v[188:189]
	v_pk_mul_f32 v[114:115], v[114:115], v[190:191]
	v_cvt_pk_f16_f32 v112, v112, v113
	v_cvt_pk_f16_f32 v113, v114, v115
	v_mov_b32_e32 v232, v112
	v_mov_b32_e32 v233, v113
	v_or_b32_e32 v112, 0x20000, v170
	v_mov_b32_e32 v113, v171
	v_lshlrev_b64 v[142:143], 1, v[112:113]
	v_pk_mul_f32 v[104:105], v[104:105], v[188:189]
	v_pk_mul_f32 v[106:107], v[106:107], v[190:191]
	v_lshl_add_u64 v[192:193], v[94:95], 0, v[142:143]
	v_cvt_pk_f16_f32 v104, v104, v105
	v_cvt_pk_f16_f32 v105, v106, v107
	v_mov_b32_e32 v236, v104
	v_mov_b32_e32 v237, v105
	v_mfma_f32_16x16x32_f16 v[104:107], v[116:119], v[16:19], v[144:147]
	v_or_b32_e32 v170, 0x30000, v170
	v_lshlrev_b64 v[116:117], 1, v[170:171]
	v_lshl_add_u64 v[118:119], v[94:95], 0, v[116:117]
	v_mfma_f32_16x16x32_f16 v[104:107], v[128:131], v[32:35], v[104:107]
	ds_bpermute_b32 v128, v150, v96 offset:8
	ds_bpermute_b32 v129, v194, v96
	v_lshl_add_u64 v[130:131], v[94:95], 0, 32
	v_mfma_f32_16x16x32_f16 v[158:161], v[212:215], v[56:59], v[196:199]
	v_lshl_add_u64 v[144:145], v[130:131], 0, v[140:141]
	s_nop 2
	v_pk_mul_f32 v[104:105], v[104:105], v[188:189]
	v_pk_mul_f32 v[106:107], v[106:107], v[190:191]
	v_cvt_pk_f16_f32 v104, v104, v105
	v_cvt_pk_f16_f32 v105, v106, v107
	v_mov_b32_e32 v240, v104
	v_mov_b32_e32 v241, v105
	v_mfma_f32_16x16x32_f16 v[104:107], v[80:83], v[36:39], v[154:157]
	ds_bpermute_b32 v118, v150, v96
	ds_bpermute_b32 v119, v150, v96 offset:4
	v_mfma_f32_16x16x32_f16 v[104:107], v[132:135], v[60:63], v[104:107]
	v_mfma_f32_16x16x32_f16 v[120:123], v[220:223], v[76:79], v[120:123]
	v_mfma_f32_16x16x32_f16 v[76:79], v[0:3], v[76:79], v[108:111]
	s_waitcnt lgkmcnt(0)
; DI unsigned pack2(float lo, float hi) { f2_t v = {lo, hi}; h2_t b = __builtin_convertvector(v, h2_t); return __builtin_bit_cast(unsigned, b); }
; DI void phase_proj(const Params& P, int l, char* smem) {
;     ...
;       for (int mt = 0; mt < 4; ++mt) {
;         float r4[4];
; #pragma unroll
;         for (int j = 0; j < 4; ++j) r4[j] = __shfl(rs[mt], 4 * g + j);
; #pragma unroll
;         for (int nt = 0; nt < 4; ++nt) {
;           const int c = c0 + nt * 16 + lr;
;           bf16_t* dst = VT + ((size_t)(br * NB + b) * 512 + c) * SEQ + s0 + mt * 16 + 4 * g;
;           *(uint2*)dst = make_uint2(pack2(acc[mt][nt][0] * r4[0], acc[mt][nt][1] * r4[1]), pack2(acc[mt][nt][2] * r4[2], acc[mt][nt][3] * r4[3]));
;         }
;       }
	s_nop 4
	v_pk_mul_f32 v[104:105], v[104:105], v[118:119]
	v_pk_mul_f32 v[106:107], v[106:107], v[128:129]
	v_cvt_pk_f16_f32 v104, v104, v105
	v_mfma_f32_16x16x32_f16 v[108:111], v[80:83], v[24:27], v[158:161]
	v_cvt_pk_f16_f32 v105, v106, v107
	v_mov_b32_e32 v230, v104
	v_mov_b32_e32 v231, v105
	v_and_b32_e32 v244, 16, v148
	v_lshrrev_b32_e32 v245, 1, v244
	v_add_u32_e32 v244, v244, v245
	v_mov_b32_e32 v245, 0
	v_lshl_add_u64 v[244:245], v[244:245], 0, v[98:99]
	v_permlane16_swap_b32_e32 v228, v230
	v_permlane16_swap_b32_e32 v229, v231
	global_store_dwordx4 v[244:245], v[228:231], off
	v_mfma_f32_16x16x32_f16 v[162:165], v[212:215], v[8:11], v[200:203]
	v_mfma_f32_16x16x32_f16 v[166:169], v[212:215], v[4:7], v[204:207]
	v_mfma_f32_16x16x32_f16 v[104:107], v[132:135], v[52:55], v[108:111]
	v_mfma_f32_16x16x32_f16 v[108:111], v[80:83], v[20:23], v[162:165]
	v_mfma_f32_16x16x32_f16 v[80:83], v[80:83], v[16:19], v[166:169]
	s_nop 5
	v_mul_f32_e64 v104, v104, v118
	v_mul_f32_e64 v105, v105, v119
	v_pk_mul_f32 v[106:107], v[106:107], v[128:129]
	v_cvt_pk_f16_f32 v104, v104, v105
	v_cvt_pk_f16_f32 v105, v106, v107
	v_mfma_f32_16x16x32_f16 v[80:83], v[132:135], v[32:35], v[80:83]
	v_mov_b32_e32 v234, v104
	v_mov_b32_e32 v235, v105
	v_and_b32_e32 v244, 16, v148
	v_lshrrev_b32_e32 v245, 1, v244
	v_add_u32_e32 v244, v244, v245
	v_mov_b32_e32 v245, 0
	v_lshl_add_u64 v[244:245], v[244:245], 0, v[144:145]
	v_permlane16_swap_b32_e32 v232, v234
	v_permlane16_swap_b32_e32 v233, v235
	global_store_dwordx4 v[244:245], v[232:235], off offset:-32
	v_mfma_f32_16x16x32_f16 v[104:107], v[132:135], v[48:51], v[108:111]
	v_mfma_f32_16x16x32_f16 v[124:127], v[220:223], v[56:59], v[124:127]
	s_nop 4
	v_mul_f32_e64 v80, v80, v118
	v_mul_f32_e64 v81, v81, v119
	v_pk_mul_f32 v[104:105], v[104:105], v[118:119]
	v_pk_mul_f32 v[106:107], v[106:107], v[128:129]
	v_mfma_f32_16x16x32_f16 v[56:59], v[0:3], v[56:59], v[72:75]
	v_cvt_pk_f16_f32 v80, v80, v81
	v_lshl_add_u64 v[108:109], v[130:131], 0, v[142:143]
	v_cvt_pk_f16_f32 v104, v104, v105
	v_pk_mul_f32 v[72:73], v[82:83], v[128:129]
	v_cvt_pk_f16_f32 v105, v106, v107
	v_cvt_pk_f16_f32 v81, v72, v73
	v_mfma_f32_16x16x32_f16 v[72:75], v[64:67], v[36:39], v[120:123]
	v_mov_b32_e32 v238, v104
	v_mov_b32_e32 v239, v105
	v_and_b32_e32 v244, 16, v148
	v_lshrrev_b32_e32 v245, 1, v244
	v_add_u32_e32 v244, v244, v245
	v_mov_b32_e32 v245, 0
	v_lshl_add_u64 v[244:245], v[244:245], 0, v[108:109]
	v_permlane16_swap_b32_e32 v236, v238
	v_permlane16_swap_b32_e32 v237, v239
	global_store_dwordx4 v[244:245], v[236:239], off offset:-32
	v_lshl_add_u64 v[104:105], v[130:131], 0, v[116:117]
	v_mov_b32_e32 v242, v80
	v_mov_b32_e32 v243, v81
	v_and_b32_e32 v244, 16, v148
	v_lshrrev_b32_e32 v245, 1, v244
	v_add_u32_e32 v244, v244, v245
	v_mov_b32_e32 v245, 0
	v_lshl_add_u64 v[244:245], v[244:245], 0, v[104:105]
	v_permlane16_swap_b32_e32 v240, v242
	v_permlane16_swap_b32_e32 v241, v243
	global_store_dwordx4 v[244:245], v[240:243], off offset:-32
	ds_bpermute_b32 v104, v150, v102
	ds_bpermute_b32 v105, v150, v102 offset:4
	ds_bpermute_b32 v106, v150, v102 offset:8
	v_mfma_f32_16x16x32_f16 v[72:75], v[68:71], v[60:63], v[72:75]
	ds_bpermute_b32 v107, v194, v102
	v_lshl_add_u64 v[102:103], v[94:95], 0, 64
	v_mfma_f32_16x16x32_f16 v[80:83], v[64:67], v[24:27], v[124:127]
	v_mfma_f32_16x16x32_f16 v[136:139], v[220:223], v[8:11], v[136:139]
	s_waitcnt lgkmcnt(2)
	s_nop 2
	v_pk_mul_f32 v[72:73], v[72:73], v[104:105]
	s_nop 0
	v_cvt_pk_f16_f32 v108, v72, v73
	v_mfma_f32_16x16x32_f16 v[112:115], v[220:223], v[4:7], v[224:227]
	s_waitcnt lgkmcnt(0)
; DI unsigned pack2(float lo, float hi) { f2_t v = {lo, hi}; h2_t b = __builtin_convertvector(v, h2_t); return __builtin_bit_cast(unsigned, b); }
; DI void phase_proj(const Params& P, int l, char* smem) {
;     ...
;       for (int mt = 0; mt < 4; ++mt) {
;         float r4[4];
; #pragma unroll
;         for (int j = 0; j < 4; ++j) r4[j] = __shfl(rs[mt], 4 * g + j);
; #pragma unroll
;         for (int nt = 0; nt < 4; ++nt) {
;           const int c = c0 + nt * 16 + lr;
;           bf16_t* dst = VT + ((size_t)(br * NB + b) * 512 + c) * SEQ + s0 + mt * 16 + 4 * g;
;           *(uint2*)dst = make_uint2(pack2(acc[mt][nt][0] * r4[0], acc[mt][nt][1] * r4[1]), pack2(acc[mt][nt][2] * r4[2], acc[mt][nt][3] * r4[3]));
;         }
;       }
	v_pk_mul_f32 v[72:73], v[74:75], v[106:107]
	s_nop 0
	v_cvt_pk_f16_f32 v109, v72, v73
	v_mfma_f32_16x16x32_f16 v[72:75], v[68:71], v[52:55], v[80:83]
	v_mov_b32_e32 v228, v108
	v_mov_b32_e32 v229, v109
	v_lshl_add_u64 v[108:109], v[102:103], 0, v[140:141]
	v_mfma_f32_16x16x32_f16 v[80:83], v[64:67], v[20:23], v[136:139]
	v_mfma_f32_16x16x32_f16 v[64:67], v[64:67], v[16:19], v[112:115]
	s_nop 3
	v_mul_f32_e64 v72, v72, v104
	v_mul_f32_e64 v73, v73, v105
	v_cvt_pk_f16_f32 v110, v72, v73
	v_pk_mul_f32 v[72:73], v[74:75], v[106:107]
	v_mfma_f32_16x16x32_f16 v[64:67], v[68:71], v[32:35], v[64:67]
	v_cvt_pk_f16_f32 v111, v72, v73
	v_mov_b32_e32 v232, v110
	v_mov_b32_e32 v233, v111
	v_mfma_f32_16x16x32_f16 v[72:75], v[68:71], v[48:51], v[80:83]
	v_lshl_add_u64 v[68:69], v[102:103], 0, v[116:117]
	s_nop 3
	v_pk_mul_f32 v[64:65], v[64:65], v[104:105]
	v_mfma_f32_16x16x32_f16 v[8:11], v[0:3], v[8:11], v[40:43]
	v_lshl_add_u64 v[80:81], v[102:103], 0, v[142:143]
	v_pk_mul_f32 v[72:73], v[72:73], v[104:105]
	v_pk_mul_f32 v[74:75], v[74:75], v[106:107]
	v_mfma_f32_16x16x32_f16 v[0:3], v[0:3], v[4:7], v[44:47]
	v_mul_f32_e64 v42, v66, v106
	v_mul_f32_e64 v43, v67, v107
	v_cvt_pk_f16_f32 v72, v72, v73
	v_cvt_pk_f16_f32 v73, v74, v75
	v_mfma_f32_16x16x32_f16 v[4:7], v[12:15], v[36:39], v[76:79]
	v_cvt_pk_f16_f32 v40, v64, v65
	v_cvt_pk_f16_f32 v41, v42, v43
	v_mov_b32_e32 v236, v72
	v_mov_b32_e32 v237, v73
	v_mov_b32_e32 v240, v40
	v_mov_b32_e32 v241, v41
	ds_bpermute_b32 v40, v150, v100
	ds_bpermute_b32 v41, v150, v100 offset:4
	ds_bpermute_b32 v36, v150, v100 offset:8
	ds_bpermute_b32 v37, v194, v100
	v_mfma_f32_16x16x32_f16 v[4:7], v[28:31], v[60:63], v[4:7]
	v_lshl_add_u64 v[38:39], v[94:95], 0, s[4:5]
	v_mfma_f32_16x16x32_f16 v[0:3], v[12:15], v[16:19], v[0:3]
	v_mfma_f32_16x16x32_f16 v[0:3], v[28:31], v[32:35], v[0:3]
	s_waitcnt lgkmcnt(2)
	s_nop 3
	v_pk_mul_f32 v[4:5], v[4:5], v[40:41]
	s_waitcnt lgkmcnt(0)
	v_pk_mul_f32 v[44:45], v[6:7], v[36:37]
	v_cvt_pk_f16_f32 v42, v4, v5
	v_mfma_f32_16x16x32_f16 v[4:7], v[12:15], v[24:27], v[56:59]
	v_cvt_pk_f16_f32 v43, v44, v45
	v_mov_b32_e32 v230, v42
	v_mov_b32_e32 v231, v43
	v_and_b32_e32 v244, 16, v148
	v_lshrrev_b32_e32 v245, 1, v244
	v_add_u32_e32 v244, v244, v245
	v_mov_b32_e32 v245, 0
	v_lshl_add_u64 v[244:245], v[244:245], 0, v[98:99]
	v_permlane16_swap_b32_e32 v228, v230
	v_permlane16_swap_b32_e32 v229, v231
	global_store_dwordx4 v[244:245], v[228:231], off offset:64
	v_lshl_add_u64 v[24:25], v[38:39], 0, v[140:141]
	v_mfma_f32_16x16x32_f16 v[4:7], v[28:31], v[52:55], v[4:7]
	v_mul_f32_e64 v0, v0, v40
	v_mul_f32_e64 v1, v1, v41
	v_pk_mul_f32 v[2:3], v[2:3], v[36:37]
	v_cvt_pk_f16_f32 v0, v0, v1
	v_cvt_pk_f16_f32 v1, v2, v3
	s_nop 2
	v_pk_mul_f32 v[4:5], v[4:5], v[40:41]
	v_pk_mul_f32 v[42:43], v[6:7], v[36:37]
	v_cvt_pk_f16_f32 v26, v4, v5
	v_mfma_f32_16x16x32_f16 v[4:7], v[12:15], v[20:23], v[8:11]
	v_cvt_pk_f16_f32 v27, v42, v43
	v_mov_b32_e32 v234, v26
	v_mov_b32_e32 v235, v27
	v_and_b32_e32 v244, 16, v148
	v_lshrrev_b32_e32 v245, 1, v244
	v_add_u32_e32 v244, v244, v245
	v_mov_b32_e32 v245, 0
	v_lshl_add_u64 v[244:245], v[244:245], 0, v[24:25]
	v_permlane16_swap_b32_e32 v232, v234
	v_permlane16_swap_b32_e32 v233, v235
	global_store_dwordx4 v[244:245], v[232:235], off offset:-32
	v_mfma_f32_16x16x32_f16 v[4:7], v[28:31], v[48:51], v[4:7]
	v_lshl_add_u64 v[8:9], v[38:39], 0, v[142:143]
	s_nop 6
	v_pk_mul_f32 v[4:5], v[4:5], v[40:41]
	v_pk_mul_f32 v[6:7], v[6:7], v[36:37]
	v_cvt_pk_f16_f32 v4, v4, v5
	v_cvt_pk_f16_f32 v5, v6, v7
	v_mov_b32_e32 v238, v4
	v_mov_b32_e32 v239, v5
	v_and_b32_e32 v244, 16, v148
	v_lshrrev_b32_e32 v245, 1, v244
	v_add_u32_e32 v244, v244, v245
	v_mov_b32_e32 v245, 0
	v_lshl_add_u64 v[244:245], v[244:245], 0, v[8:9]
	v_permlane16_swap_b32_e32 v236, v238
	v_permlane16_swap_b32_e32 v237, v239
	global_store_dwordx4 v[244:245], v[236:239], off offset:-32
	v_lshl_add_u64 v[4:5], v[38:39], 0, v[116:117]
	v_mov_b32_e32 v242, v0
	v_mov_b32_e32 v243, v1
	v_and_b32_e32 v244, 16, v148
	v_lshrrev_b32_e32 v245, 1, v244
	v_add_u32_e32 v244, v244, v245
	v_mov_b32_e32 v245, 0
	v_lshl_add_u64 v[244:245], v[244:245], 0, v[4:5]
	v_permlane16_swap_b32_e32 v240, v242
	v_permlane16_swap_b32_e32 v241, v243
	global_store_dwordx4 v[244:245], v[240:243], off offset:-32
	s_branch .LBB0_636
